# sequential scans (gated-DeltaNet, mLSTM): state-decay multiply back in front of S3, small per-step loads issued ahead of the next-chunk prefetch so the first gate conversion no longer drains it
# speedup vs baseline: 1.5357x; 1.0120x over previous
.LBB0_505:
	v_lshl_add_u64 v[52:53], s[30:31], 0, v[128:129]
	v_add_co_u32_e32 v54, vcc, 0x1000, v52
	s_movk_i32 s0, 0x6000
	s_nop 0
	v_addc_co_u32_e32 v55, vcc, 0, v53, vcc
	v_add_co_u32_e32 v56, vcc, s48, v52
	s_nop 1
	v_addc_co_u32_e32 v57, vcc, 0, v53, vcc
	global_load_ushort v84, v[54:55], off offset:1536
	global_load_ushort v157, v[54:55], off offset:1568
	global_load_ushort v80, v[54:55], off offset:1600
	global_load_ushort v85, v[54:55], off offset:1632
	global_load_ushort v154, v[56:57], off offset:3840
	global_load_ushort v153, v[56:57], off offset:3872
	global_load_ushort v156, v[56:57], off offset:3904
	global_load_ushort v155, v[56:57], off offset:3936
	v_add_co_u32_e32 v54, vcc, s56, v52
	s_nop 1
	v_addc_co_u32_e32 v55, vcc, 0, v53, vcc
	v_add_co_u32_e32 v52, vcc, s0, v52
	s_nop 1
	v_addc_co_u32_e32 v53, vcc, 0, v53, vcc
	global_load_ushort v150, v[54:55], off offset:2048
	global_load_ushort v149, v[54:55], off offset:2080
	global_load_ushort v152, v[54:55], off offset:2112
	global_load_ushort v151, v[54:55], off offset:2144
	global_load_ushort v146, v[52:53], off offset:256
	global_load_ushort v112, v[52:53], off offset:288
	global_load_ushort v148, v[52:53], off offset:320
	global_load_ushort v147, v[52:53], off offset:352
	s_cmp_eq_u32 s18, 1
	s_cbranch_scc1 .Lmls_pf_skip
	v_lshl_add_u64 v[0:1], s[30:31], 0, v[108:109]
	v_lshl_add_u64 v[4:5], s[30:31], 0, v[110:111]
	v_lshl_add_u64 v[8:9], s[30:31], 0, v[116:117]
	v_lshl_add_u64 v[12:13], s[30:31], 0, v[118:119]
	v_lshl_add_u64 v[16:17], s[30:31], 0, v[120:121]
	v_lshl_add_u64 v[20:21], s[30:31], 0, v[122:123]
	v_lshl_add_u64 v[28:29], s[30:31], 0, v[104:105]
	v_lshl_add_u64 v[32:33], s[30:31], 0, v[106:107]
	global_load_dwordx4 v[0:3], v[0:1], off
	s_nop 0
	global_load_dwordx4 v[4:7], v[4:5], off
	s_nop 0
	global_load_dwordx4 v[8:11], v[8:9], off
	s_nop 0
	global_load_dwordx4 v[12:15], v[12:13], off
	s_nop 0
	global_load_dwordx4 v[16:19], v[16:17], off
	s_nop 0
	global_load_dwordx4 v[20:23], v[20:21], off
	s_nop 0
	global_load_dwordx4 v[28:31], v[28:29], off
	s_nop 0
	global_load_dwordx4 v[32:35], v[32:33], off
	s_and_saveexec_b64 s[16:17], s[10:11]
	s_cbranch_execz .LBB0_504
	v_lshl_add_u64 v[24:25], s[30:31], 0, v[124:125]
	global_load_dwordx4 v[24:27], v[24:25], off

.Lmls_pf_skip:
	ds_read_b128 v[52:55], v137 offset:46080
	ds_read_b128 v[56:59], v136
	ds_read_b128 v[60:63], v136 offset:16
	ds_read_b128 v[64:67], v137 offset:46096
	ds_read_b128 v[68:71], v137 offset:46112
	ds_read_b128 v[72:75], v137 offset:46128
	s_waitcnt lgkmcnt(4)
	v_fma_mix_f32 v52, v52, v56, 0 op_sel_hi:[0,1,0]
	v_fma_mix_f32 v52, v53, v56, v52 op_sel:[0,1,0] op_sel_hi:[0,1,0]
	v_fma_mix_f32 v52, v54, v57, v52 op_sel_hi:[0,1,0]
	v_fma_mix_f32 v52, v55, v57, v52 op_sel:[0,1,0] op_sel_hi:[0,1,0]
	s_waitcnt lgkmcnt(2)
	v_fma_mix_f32 v52, v64, v58, v52 op_sel_hi:[0,1,0]
	v_fma_mix_f32 v52, v65, v58, v52 op_sel:[0,1,0] op_sel_hi:[0,1,0]
	v_fma_mix_f32 v52, v66, v59, v52 op_sel_hi:[0,1,0]
	v_fma_mix_f32 v52, v67, v59, v52 op_sel:[0,1,0] op_sel_hi:[0,1,0]
	s_waitcnt lgkmcnt(1)
	v_fma_mix_f32 v52, v68, v60, v52 op_sel_hi:[0,1,0]
	v_fma_mix_f32 v52, v69, v60, v52 op_sel:[0,1,0] op_sel_hi:[0,1,0]
	v_fma_mix_f32 v52, v70, v61, v52 op_sel_hi:[0,1,0]
	v_fma_mix_f32 v52, v71, v61, v52 op_sel:[0,1,0] op_sel_hi:[0,1,0]
	s_waitcnt lgkmcnt(0)
	v_fma_mix_f32 v52, v72, v62, v52 op_sel_hi:[0,1,0]
	v_fma_mix_f32 v52, v73, v62, v52 op_sel:[0,1,0] op_sel_hi:[0,1,0]
	v_fma_mix_f32 v52, v74, v63, v52 op_sel_hi:[0,1,0]
	v_fma_mix_f32 v52, v75, v63, v52 op_sel:[0,1,0] op_sel_hi:[0,1,0]
	ds_bpermute_b32 v53, v138, v52
	s_waitcnt lgkmcnt(0)
	v_add_f32_e32 v52, v52, v53
	ds_bpermute_b32 v53, v139, v52
	s_and_saveexec_b64 s[16:17], s[12:13]
	s_cbranch_execz .LBB0_507
	s_waitcnt lgkmcnt(0)
	v_add_f32_e32 v52, v52, v53
	ds_write_b32 v142, v52 offset:46336

.LBB0_523:
	v_lshl_add_u64 v[96:97], s[30:31], 0, v[144:145]
	s_movk_i32 s0, 0x1000
	v_add_co_u32_e32 v172, vcc, s0, v96
	s_movk_i32 s0, 0x5000
	s_nop 0
	v_addc_co_u32_e32 v173, vcc, 0, v97, vcc
	v_add_co_u32_e32 v170, vcc, s48, v96
	s_add_u32 s12, s30, s2
	s_nop 0
	v_addc_co_u32_e32 v171, vcc, 0, v97, vcc
	v_add_co_u32_e32 v168, vcc, s56, v96
	s_addc_u32 s13, s31, s3
	s_nop 0
	v_addc_co_u32_e32 v169, vcc, 0, v97, vcc
	v_add_co_u32_e32 v166, vcc, s0, v96
	global_load_dword v112, v192, s[12:13] sc1
	s_nop 0
	v_addc_co_u32_e32 v167, vcc, 0, v97, vcc
	global_load_ushort v234, v[172:173], off offset:256
	global_load_ushort v233, v[172:173], off offset:288
	global_load_ushort v232, v[172:173], off offset:320
	global_load_ushort v231, v[172:173], off offset:352
	global_load_ushort v230, v[170:171], off offset:2560
	global_load_ushort v229, v[170:171], off offset:2592
	global_load_ushort v228, v[170:171], off offset:2624
	global_load_ushort v227, v[170:171], off offset:2656
	global_load_ushort v226, v[168:169], off offset:768
	global_load_ushort v225, v[168:169], off offset:800
	global_load_ushort v224, v[168:169], off offset:832
	global_load_ushort v223, v[168:169], off offset:864
	global_load_ushort v181, v[166:167], off offset:3072
	global_load_ushort v180, v[166:167], off offset:3104
	global_load_ushort v179, v[166:167], off offset:3136
	global_load_ushort v178, v[166:167], off offset:3168
	s_cmpk_gt_u32 s15, 0x7d
	s_cbranch_scc1 .Lscan_pfA_skip
	v_add_co_u32_e32 v40, vcc, 0xc814000, v164
	s_nop 1
	v_addc_co_u32_e32 v41, vcc, 0, v165, vcc
	v_add_co_u32_e32 v44, vcc, 0xc814000, v162
	s_nop 1
	v_addc_co_u32_e32 v45, vcc, 0, v163, vcc
	v_add_co_u32_e32 v48, vcc, 0xc814000, v160
	global_load_dwordx4 v[40:43], v[40:41], off
	s_nop 0
	global_load_dwordx4 v[44:47], v[44:45], off
	v_addc_co_u32_e32 v49, vcc, 0, v161, vcc
	v_add_co_u32_e32 v52, vcc, 0xc814000, v158
	s_nop 1
	v_addc_co_u32_e32 v53, vcc, 0, v159, vcc
	v_add_co_u32_e32 v56, vcc, 0xc814000, v156
	global_load_dwordx4 v[48:51], v[48:49], off
	s_nop 0
	global_load_dwordx4 v[52:55], v[52:53], off
	v_addc_co_u32_e32 v57, vcc, 0, v157, vcc
	v_add_co_u32_e32 v60, vcc, 0xc814000, v154
	s_nop 1
	v_addc_co_u32_e32 v61, vcc, 0, v155, vcc
	v_add_co_u32_e32 v64, vcc, 0xc814000, v152
	global_load_dwordx4 v[56:59], v[56:57], off
	s_nop 0
	global_load_dwordx4 v[60:63], v[60:61], off
	v_addc_co_u32_e32 v65, vcc, 0, v153, vcc
	v_add_co_u32_e32 v68, vcc, 0xc814000, v150
	s_nop 1
	v_addc_co_u32_e32 v69, vcc, 0, v151, vcc
	v_add_co_u32_e32 v72, vcc, 0xc814000, v148
	global_load_dwordx4 v[64:67], v[64:65], off
	s_nop 0
	global_load_dwordx4 v[68:71], v[68:69], off
	v_addc_co_u32_e32 v73, vcc, 0, v149, vcc
	v_add_co_u32_e32 v76, vcc, 0xc814000, v146
	s_nop 1
	v_addc_co_u32_e32 v77, vcc, 0, v147, vcc
	global_load_dwordx4 v[72:75], v[72:73], off
	s_nop 0
	global_load_dwordx4 v[76:79], v[76:77], off
.Lscan_pfA_skip:
	s_mov_b32 s0, 0x358637bd
	ds_read_b128 v[108:111], v116 offset:46080
	ds_read_b128 v[240:243], v117
	ds_read_b128 v[244:247], v117 offset:2304
	ds_read_b128 v[252:255], v117 offset:4608
	s_waitcnt lgkmcnt(2)
	v_mfma_f32_16x16x32_f16 v[236:239], v[108:111], v[240:243], 0
	ds_read_b128 v[240:243], v117 offset:6912
	ds_read_b128 v[174:177], v116 offset:46144
	s_waitcnt lgkmcnt(3)
	v_mfma_f32_16x16x32_f16 v[104:107], v[108:111], v[244:247], 0
	ds_read_b128 v[244:247], v117 offset:64
	s_waitcnt lgkmcnt(3)
	v_mfma_f32_16x16x32_f16 v[100:103], v[108:111], v[252:255], 0
	ds_read_b128 v[252:255], v117 offset:2368
	s_waitcnt lgkmcnt(3)
	v_mfma_f32_16x16x32_f16 v[96:99], v[108:111], v[240:243], 0
	ds_read_b128 v[240:243], v117 offset:4672
	s_waitcnt lgkmcnt(2)
	v_mfma_f32_16x16x32_f16 v[236:239], v[174:177], v[244:247], v[236:239]
	ds_read_b128 v[244:247], v117 offset:6976
	s_waitcnt lgkmcnt(2)
	v_mfma_f32_16x16x32_f16 v[104:107], v[174:177], v[252:255], v[104:107]
	s_waitcnt lgkmcnt(1)
	v_mfma_f32_16x16x32_f16 v[100:103], v[174:177], v[240:243], v[100:103]
	s_waitcnt lgkmcnt(0)
	v_mfma_f32_16x16x32_f16 v[96:99], v[174:177], v[244:247], v[96:99]
	ds_read_b64 v[108:109], v214 offset:9216
	s_waitcnt lgkmcnt(0)
	v_cvt_f32_f16_e32 v110, v108
	v_cvt_f32_f16_sdwa v108, v108 dst_sel:DWORD dst_unused:UNUSED_PAD src0_sel:WORD_1
	v_sub_f32_e32 v110, v110, v236
	v_sub_f32_e32 v108, v108, v237
	v_med3_f32 v108, v108, s57, v194
	v_cvt_f16_f32_e32 v108, v108
	v_med3_f32 v110, v110, s57, v194
	v_cvt_f16_f32_e32 v110, v110
	ds_write_b16 v215, v108 offset:55440
	v_cvt_f32_f16_e32 v108, v109
	ds_write_b16 v215, v110 offset:55296
	v_sub_f32_e32 v108, v108, v238
	v_med3_f32 v108, v108, s57, v194
	v_cvt_f16_f32_e32 v108, v108
	ds_write_b16 v215, v108 offset:55584
	v_cvt_f32_f16_sdwa v108, v109 dst_sel:DWORD dst_unused:UNUSED_PAD src0_sel:WORD_1
	v_sub_f32_e32 v108, v108, v239
	v_med3_f32 v108, v108, s57, v194
	v_cvt_f16_f32_e32 v108, v108
	ds_write_b16 v215, v108 offset:55728
	ds_read_b64 v[108:109], v214 offset:11520
	s_waitcnt lgkmcnt(0)
	v_cvt_f32_f16_e32 v110, v108
	v_sub_f32_e32 v104, v110, v104
	v_med3_f32 v104, v104, s57, v194
	v_cvt_f16_f32_e32 v104, v104
	ds_write_b16 v215, v104 offset:55328
	v_cvt_f32_f16_sdwa v104, v108 dst_sel:DWORD dst_unused:UNUSED_PAD src0_sel:WORD_1
	v_sub_f32_e32 v104, v104, v105
	v_med3_f32 v104, v104, s57, v194
	v_cvt_f16_f32_e32 v104, v104
	ds_write_b16 v216, v104 offset:55440
	v_cvt_f32_f16_e32 v104, v109
	v_sub_f32_e32 v104, v104, v106
	v_med3_f32 v104, v104, s57, v194
	v_cvt_f16_f32_e32 v104, v104
	ds_write_b16 v216, v104 offset:55584
	v_cvt_f32_f16_sdwa v104, v109 dst_sel:DWORD dst_unused:UNUSED_PAD src0_sel:WORD_1
	v_sub_f32_e32 v104, v104, v107
	v_med3_f32 v104, v104, s57, v194
	v_cvt_f16_f32_e32 v104, v104
	ds_write_b16 v216, v104 offset:55728
	ds_read_b64 v[104:105], v214 offset:13824
	s_waitcnt lgkmcnt(0)
	v_cvt_f32_f16_e32 v106, v104
	v_sub_f32_e32 v100, v106, v100
	v_med3_f32 v100, v100, s57, v194
	v_cvt_f16_f32_e32 v100, v100
	ds_write_b16 v215, v100 offset:55360
	v_cvt_f32_f16_sdwa v100, v104 dst_sel:DWORD dst_unused:UNUSED_PAD src0_sel:WORD_1
	v_sub_f32_e32 v100, v100, v101
	v_med3_f32 v100, v100, s57, v194
	v_cvt_f16_f32_e32 v100, v100
	ds_write_b16 v217, v100 offset:55440
	v_cvt_f32_f16_e32 v100, v105
	v_sub_f32_e32 v100, v100, v102
	v_med3_f32 v100, v100, s57, v194
	v_cvt_f16_f32_e32 v100, v100
	ds_write_b16 v217, v100 offset:55584
	v_cvt_f32_f16_sdwa v100, v105 dst_sel:DWORD dst_unused:UNUSED_PAD src0_sel:WORD_1
	v_sub_f32_e32 v100, v100, v103
	v_med3_f32 v100, v100, s57, v194
	v_cvt_f16_f32_e32 v100, v100
	ds_write_b16 v217, v100 offset:55728
	ds_read_b64 v[100:101], v214 offset:16128
	s_waitcnt lgkmcnt(0)
	v_cvt_f32_f16_e32 v102, v100
	v_sub_f32_e32 v96, v102, v96
	v_med3_f32 v96, v96, s57, v194
	v_cvt_f16_f32_e32 v96, v96
	ds_write_b16 v215, v96 offset:55392
	v_cvt_f32_f16_sdwa v96, v100 dst_sel:DWORD dst_unused:UNUSED_PAD src0_sel:WORD_1
	v_sub_f32_e32 v96, v96, v97
	v_med3_f32 v96, v96, s57, v194
	v_cvt_f16_f32_e32 v96, v96
	ds_write_b16 v218, v96 offset:55440
	v_cvt_f32_f16_e32 v96, v101
	v_sub_f32_e32 v96, v96, v98
	v_med3_f32 v96, v96, s57, v194
	v_cvt_f16_f32_e32 v96, v96
	ds_write_b16 v218, v96 offset:55584
	v_cvt_f32_f16_sdwa v96, v101 dst_sel:DWORD dst_unused:UNUSED_PAD src0_sel:WORD_1
	v_sub_f32_e32 v96, v96, v99
	v_med3_f32 v96, v96, s57, v194
	v_cvt_f16_f32_e32 v96, v96
	ds_write_b16 v218, v96 offset:55728
	s_waitcnt lgkmcnt(0)
	s_barrier
	ds_write_b128 v115, v[0:3]
	ds_write_b128 v209, v[4:7]
	ds_write_b128 v219, v[8:11]
	ds_write_b128 v210, v[12:15]
	s_waitcnt vmcnt(15)
	v_cvt_f32_f16_e32 v235, v234
	global_load_dword v234, v[118:119], off
	ds_read_b128 v[174:177], v116 offset:27648
	ds_read_b128 v[240:243], v117 offset:46080
	ds_read_b128 v[244:247], v117 offset:48384
	ds_read_b128 v[252:255], v117 offset:50688
	s_waitcnt lgkmcnt(2)
	v_mfma_f32_16x16x32_f16 v[108:111], v[174:177], v[240:243], 0
	ds_read_b128 v[240:243], v117 offset:52992
	ds_read_b128 v[236:239], v116 offset:27712
	s_waitcnt lgkmcnt(3)
	v_mfma_f32_16x16x32_f16 v[104:107], v[174:177], v[244:247], 0
	ds_read_b128 v[244:247], v117 offset:46144
	s_waitcnt lgkmcnt(3)
	v_mfma_f32_16x16x32_f16 v[100:103], v[174:177], v[252:255], 0
	ds_read_b128 v[252:255], v117 offset:48448
	s_waitcnt lgkmcnt(3)
	v_mfma_f32_16x16x32_f16 v[96:99], v[174:177], v[240:243], 0
	ds_read_b128 v[240:243], v117 offset:50752
	s_waitcnt lgkmcnt(2)
	v_mfma_f32_16x16x32_f16 v[108:111], v[236:239], v[244:247], v[108:111]
	ds_read_b128 v[244:247], v117 offset:53056
	ds_read_b128 v[174:177], v116 offset:18432
	s_waitcnt lgkmcnt(3)
	v_mfma_f32_16x16x32_f16 v[104:107], v[236:239], v[252:255], v[104:107]
	ds_read_b128 v[252:255], v117 offset:55296
	s_waitcnt lgkmcnt(3)
	v_mfma_f32_16x16x32_f16 v[100:103], v[236:239], v[240:243], v[100:103]
	ds_read_b128 v[240:243], v117 offset:57600
	s_waitcnt lgkmcnt(3)
	v_mfma_f32_16x16x32_f16 v[96:99], v[236:239], v[244:247], v[96:99]
	ds_read_b128 v[244:247], v117 offset:59904
	s_waitcnt lgkmcnt(2)
	v_mfma_f32_16x16x32_f16 v[108:111], v[174:177], v[252:255], v[108:111]
	ds_read_b128 v[252:255], v117 offset:62208
	ds_read_b128 v[236:239], v116 offset:18496
	s_waitcnt lgkmcnt(3)
	v_mfma_f32_16x16x32_f16 v[104:107], v[174:177], v[240:243], v[104:107]
	ds_read_b128 v[240:243], v117 offset:55360
	s_waitcnt lgkmcnt(3)
	v_mfma_f32_16x16x32_f16 v[100:103], v[174:177], v[244:247], v[100:103]
	ds_read_b128 v[244:247], v117 offset:57664
	s_waitcnt lgkmcnt(3)
	v_mfma_f32_16x16x32_f16 v[96:99], v[174:177], v[252:255], v[96:99]
	ds_read_b128 v[252:255], v117 offset:59968
	s_waitcnt lgkmcnt(2)
	v_mfma_f32_16x16x32_f16 v[108:111], v[236:239], v[240:243], v[108:111]
	ds_read_b128 v[240:243], v117 offset:62272
	s_waitcnt lgkmcnt(2)
	v_mfma_f32_16x16x32_f16 v[104:107], v[236:239], v[244:247], v[104:107]
	s_waitcnt lgkmcnt(1)
	v_mfma_f32_16x16x32_f16 v[100:103], v[236:239], v[252:255], v[100:103]
	s_waitcnt lgkmcnt(0)
	v_mfma_f32_16x16x32_f16 v[96:99], v[236:239], v[240:243], v[96:99]
	v_mul_f32_e32 v236, 0xbfb8aa3b, v235
	v_exp_f32_e32 v236, v236
	v_mov_b32_e32 v174, v108
	v_mov_b32_e32 v175, v104
	v_pk_mul_f32 v[176:177], v[174:175], v[174:175]
	v_add_f32_e32 v236, 1.0, v236
	v_div_scale_f32 v237, s[8:9], v236, v236, v235
	v_rcp_f32_e32 v238, v237
	v_mov_b32_e32 v174, v100
	v_mov_b32_e32 v175, v96
	v_pk_mul_f32 v[174:175], v[174:175], v[174:175]
	v_fma_f32 v239, -v237, v238, 1.0
	v_fmac_f32_e32 v238, v239, v238
	v_div_scale_f32 v239, vcc, v235, v236, v235
	v_mul_f32_e32 v240, v239, v238
	v_fma_f32 v241, -v237, v240, v239
	v_fmac_f32_e32 v240, v241, v238
	v_fma_f32 v237, -v237, v240, v239
	v_div_fmas_f32 v237, v237, v238, v240
	v_div_fixup_f32 v235, v237, v236, v235
	s_waitcnt vmcnt(15)
	v_cvt_f32_f16_e32 v236, v233
	global_load_dword v233, v[118:119], off offset:64
	v_mul_f32_e32 v237, 0xbfb8aa3b, v236
	v_exp_f32_e32 v237, v237
	s_nop 0
	v_add_f32_e32 v237, 1.0, v237
	v_div_scale_f32 v238, s[8:9], v237, v237, v236
	v_rcp_f32_e32 v239, v238
	s_nop 0
	v_fma_f32 v240, -v238, v239, 1.0
	v_fmac_f32_e32 v239, v240, v239
	v_div_scale_f32 v240, vcc, v236, v237, v236
	v_mul_f32_e32 v241, v240, v239
	v_fma_f32 v242, -v238, v241, v240
	v_fmac_f32_e32 v241, v242, v239
	v_fma_f32 v238, -v238, v241, v240
	v_div_fmas_f32 v238, v238, v239, v241
	v_div_fixup_f32 v242, v238, v237, v236
	s_waitcnt vmcnt(15)
	v_cvt_f32_f16_e32 v236, v232
	global_load_dword v232, v[118:119], off offset:128
	v_mul_f32_e32 v237, 0xbfb8aa3b, v236
	v_exp_f32_e32 v237, v237
	s_nop 0
	v_add_f32_e32 v237, 1.0, v237
	v_div_scale_f32 v238, s[8:9], v237, v237, v236
	v_rcp_f32_e32 v239, v238
	s_nop 0
	v_fma_f32 v240, -v238, v239, 1.0
	v_fmac_f32_e32 v239, v240, v239
	v_div_scale_f32 v240, vcc, v236, v237, v236
	v_mul_f32_e32 v241, v240, v239
	v_fma_f32 v243, -v238, v241, v240
	v_fmac_f32_e32 v241, v243, v239
	v_fma_f32 v238, -v238, v241, v240
	v_div_fmas_f32 v238, v238, v239, v241
	v_div_fixup_f32 v243, v238, v237, v236
	s_waitcnt vmcnt(15)
	v_cvt_f32_f16_e32 v236, v231
	global_load_dword v231, v[118:119], off offset:192
	v_mul_f32_e32 v237, 0xbfb8aa3b, v236
	v_exp_f32_e32 v237, v237
	s_nop 0
	v_add_f32_e32 v237, 1.0, v237
	v_div_scale_f32 v238, s[8:9], v237, v237, v236
	v_rcp_f32_e32 v239, v238
	s_nop 0
	v_fma_f32 v240, -v238, v239, 1.0
	v_fmac_f32_e32 v239, v240, v239
	v_div_scale_f32 v240, vcc, v236, v237, v236
	v_mul_f32_e32 v241, v240, v239
	v_fma_f32 v244, -v238, v241, v240
	v_fmac_f32_e32 v241, v244, v239
	v_fma_f32 v238, -v238, v241, v240
	v_div_fmas_f32 v238, v238, v239, v241
	v_div_fixup_f32 v244, v238, v237, v236
	v_mov_b32_e32 v236, v109
	v_mov_b32_e32 v237, v105
	v_pk_mul_f32 v[236:237], v[236:237], v[236:237]
	v_mov_b32_e32 v238, v101
	v_mov_b32_e32 v239, v97
	v_pk_mul_f32 v[238:239], v[238:239], v[238:239]
	v_mov_b32_e32 v240, v236
	v_mov_b32_e32 v241, v176
	v_mov_b32_e32 v176, v237
	v_pk_add_f32 v[176:177], v[240:241], v[176:177]
	v_mov_b32_e32 v236, v238
	v_mov_b32_e32 v237, v174
	v_pk_add_f32 v[176:177], v[176:177], v[236:237]
	v_mov_b32_e32 v174, v239
	v_pk_add_f32 v[174:175], v[176:177], v[174:175]
	s_nop 1
	v_mov_b32_dpp v177, v175 quad_perm:[1,0,3,2] row_mask:0xf bank_mask:0xf bound_ctrl:1
	v_mov_b32_dpp v176, v174 quad_perm:[1,0,3,2] row_mask:0xf bank_mask:0xf bound_ctrl:1
	v_pk_add_f32 v[174:175], v[174:175], v[176:177]
	s_nop 1
	v_mov_b32_dpp v177, v175 quad_perm:[2,3,0,1] row_mask:0xf bank_mask:0xf bound_ctrl:1
	v_mov_b32_dpp v176, v174 quad_perm:[2,3,0,1] row_mask:0xf bank_mask:0xf bound_ctrl:1
	v_pk_add_f32 v[174:175], v[174:175], v[176:177]
	s_nop 1
	v_mov_b32_dpp v177, v175 row_ror:4 row_mask:0xf bank_mask:0xf bound_ctrl:1
	v_mov_b32_dpp v176, v174 row_ror:4 row_mask:0xf bank_mask:0xf bound_ctrl:1
	v_pk_add_f32 v[174:175], v[174:175], v[176:177]
	s_nop 1
	v_mov_b32_dpp v177, v175 row_ror:8 row_mask:0xf bank_mask:0xf bound_ctrl:1
	v_mov_b32_dpp v176, v174 row_ror:8 row_mask:0xf bank_mask:0xf bound_ctrl:1
	v_pk_add_f32 v[176:177], v[174:175], v[176:177]
	v_mov_b64_e32 v[174:175], s[0:1]
	s_mov_b32 s0, 0x3c800000
	v_pk_fma_f32 v[176:177], v[176:177], s[0:1], v[174:175] op_sel_hi:[1,0,0]
	s_nop 0
	v_mul_f32_e32 v236, 0x4b800000, v177
	v_cmp_gt_f32_e64 s[8:9], s49, v177
	v_cmp_gt_f32_e32 vcc, s49, v176
	s_nop 0
	v_cndmask_b32_e64 v177, v177, v236, s[8:9]
	v_rsq_f32_e32 v177, v177
	s_nop 0
	v_mul_f32_e32 v236, 0x45800000, v177
	v_cndmask_b32_e64 v177, v177, v236, s[8:9]
	v_mul_f32_e32 v96, v96, v177
	v_mul_f32_e32 v100, v100, v177
	s_waitcnt vmcnt(1)
	v_mul_f32_e32 v100, v232, v100
	v_mul_f32_e32 v100, v243, v100
	v_med3_f32 v100, v100, s57, v194
	s_waitcnt vmcnt(0)
	v_mul_f32_e32 v96, v231, v96
	v_mul_f32_e32 v96, v244, v96
	v_med3_f32 v96, v96, s57, v194
	v_cvt_f16_f32_e32 v96, v96
	v_cvt_f16_f32_e32 v100, v100
	v_mul_f32_e32 v108, v108, v177
	v_mul_f32_e32 v108, v234, v108
	global_store_short v[172:173], v96, off offset:352
	v_mul_f32_e32 v96, 0x4b800000, v176
	v_cndmask_b32_e32 v96, v176, v96, vcc
	v_rsq_f32_e32 v96, v96
	v_mul_f32_e32 v108, v235, v108
	v_med3_f32 v108, v108, s57, v194
	global_store_short v[172:173], v100, off offset:320
	v_mul_f32_e32 v100, 0x45800000, v96
	v_cvt_f16_f32_e32 v108, v108
	v_cndmask_b32_e32 v96, v96, v100, vcc
	v_cvt_f32_f16_e32 v100, v230
	v_mul_f32_e32 v104, v104, v177
	v_mul_f32_e32 v104, v233, v104
	global_store_short v[172:173], v108, off offset:256
	v_mul_f32_e32 v104, v242, v104
	v_mul_f32_e32 v108, 0xbfb8aa3b, v100
	v_med3_f32 v104, v104, s57, v194
	v_exp_f32_e32 v108, v108
	v_cvt_f16_f32_e32 v104, v104
	v_mul_f32_e32 v101, v101, v96
	v_mul_f32_e32 v101, v232, v101
	v_add_f32_e32 v108, 1.0, v108
	global_store_short v[172:173], v104, off offset:288
	v_mul_f32_e32 v104, v109, v96
	v_div_scale_f32 v109, s[8:9], v108, v108, v100
	v_rcp_f32_e32 v172, v109
	v_mul_f32_e32 v104, v234, v104
	v_fma_f32 v173, -v109, v172, 1.0
	v_fmac_f32_e32 v172, v173, v172
	v_div_scale_f32 v173, vcc, v100, v108, v100
	v_mul_f32_e32 v176, v173, v172
	v_fma_f32 v177, -v109, v176, v173
	v_fmac_f32_e32 v176, v177, v172
	v_fma_f32 v109, -v109, v176, v173
	v_div_fmas_f32 v109, v109, v172, v176
	v_div_fixup_f32 v100, v109, v108, v100
	v_mul_f32_e32 v100, v100, v104
	v_med3_f32 v100, v100, s57, v194
	v_cvt_f16_f32_e32 v100, v100
	v_mul_f32_e32 v104, v105, v96
	v_mul_f32_e32 v104, v233, v104
	v_mul_f32_e32 v96, v97, v96
	global_store_short v[170:171], v100, off offset:2560
	v_cvt_f32_f16_e32 v100, v229
	v_mul_f32_e32 v96, v231, v96
	v_mul_f32_e32 v105, 0xbfb8aa3b, v100
	v_exp_f32_e32 v105, v105
	s_nop 0
	v_add_f32_e32 v105, 1.0, v105
	v_div_scale_f32 v108, s[8:9], v105, v105, v100
	v_rcp_f32_e32 v109, v108
	s_nop 0
	v_fma_f32 v172, -v108, v109, 1.0
	v_fmac_f32_e32 v109, v172, v109
	v_div_scale_f32 v172, vcc, v100, v105, v100
	v_mul_f32_e32 v173, v172, v109
	v_fma_f32 v176, -v108, v173, v172
	v_fmac_f32_e32 v173, v176, v109
	v_fma_f32 v108, -v108, v173, v172
	v_div_fmas_f32 v108, v108, v109, v173
	v_div_fixup_f32 v100, v108, v105, v100
	v_mul_f32_e32 v100, v100, v104
	v_med3_f32 v100, v100, s57, v194
	v_cvt_f16_f32_e32 v100, v100
	global_store_short v[170:171], v100, off offset:2592
	v_cvt_f32_f16_e32 v100, v228
	v_mul_f32_e32 v104, 0xbfb8aa3b, v100
	v_exp_f32_e32 v104, v104
	s_nop 0
	v_add_f32_e32 v104, 1.0, v104
	v_div_scale_f32 v105, s[8:9], v104, v104, v100
	v_rcp_f32_e32 v108, v105
	s_nop 0
	v_fma_f32 v109, -v105, v108, 1.0
	v_fmac_f32_e32 v108, v109, v108
	v_div_scale_f32 v109, vcc, v100, v104, v100
	v_mul_f32_e32 v172, v109, v108
	v_fma_f32 v173, -v105, v172, v109
	v_fmac_f32_e32 v172, v173, v108
	v_fma_f32 v105, -v105, v172, v109
	v_div_fmas_f32 v105, v105, v108, v172
	v_div_fixup_f32 v100, v105, v104, v100
	v_mul_f32_e32 v100, v100, v101
	v_med3_f32 v100, v100, s57, v194
	v_cvt_f16_f32_e32 v100, v100
	global_store_short v[170:171], v100, off offset:2624
	v_cvt_f32_f16_e32 v100, v227
	v_mul_f32_e32 v97, 0xbfb8aa3b, v100
	v_exp_f32_e32 v97, v97
	s_nop 0
	v_add_f32_e32 v97, 1.0, v97
	v_div_scale_f32 v101, s[8:9], v97, v97, v100
	v_rcp_f32_e32 v104, v101
	s_nop 0
	v_fma_f32 v105, -v101, v104, 1.0
	v_fmac_f32_e32 v104, v105, v104
	v_div_scale_f32 v105, vcc, v100, v97, v100
	v_mul_f32_e32 v108, v105, v104
	v_fma_f32 v109, -v101, v108, v105
	v_fmac_f32_e32 v108, v109, v104
	v_fma_f32 v101, -v101, v108, v105
	v_div_fmas_f32 v101, v101, v104, v108
	v_cvt_f32_f16_e32 v104, v226
	v_div_fixup_f32 v97, v101, v97, v100
	v_mul_f32_e32 v96, v97, v96
	v_med3_f32 v96, v96, s57, v194
	v_mul_f32_e32 v105, 0xbfb8aa3b, v104
	v_exp_f32_e32 v105, v105
	v_cvt_f16_f32_e32 v96, v96
	v_mov_b32_e32 v97, v106
	v_add_f32_e32 v105, 1.0, v105
	v_div_scale_f32 v108, s[8:9], v105, v105, v104
	v_rcp_f32_e32 v109, v108
	global_store_short v[170:171], v96, off offset:2656
	v_mov_b32_e32 v96, v110
	v_pk_mul_f32 v[100:101], v[96:97], v[96:97]
	v_fma_f32 v170, -v108, v109, 1.0
	v_fmac_f32_e32 v109, v170, v109
	v_div_scale_f32 v170, vcc, v104, v105, v104
	v_mul_f32_e32 v171, v170, v109
	v_fma_f32 v172, -v108, v171, v170
	v_fmac_f32_e32 v171, v172, v109
	v_fma_f32 v108, -v108, v171, v170
	v_div_fmas_f32 v108, v108, v109, v171
	v_div_fixup_f32 v172, v108, v105, v104
	v_cvt_f32_f16_e32 v104, v225
	v_mov_b32_e32 v96, v102
	v_mov_b32_e32 v97, v98
	v_pk_mul_f32 v[96:97], v[96:97], v[96:97]
	v_mul_f32_e32 v105, 0xbfb8aa3b, v104
	v_exp_f32_e32 v105, v105
	s_nop 0
	v_add_f32_e32 v105, 1.0, v105
	v_div_scale_f32 v108, s[8:9], v105, v105, v104
	v_rcp_f32_e32 v109, v108
	s_nop 0
	v_fma_f32 v170, -v108, v109, 1.0
	v_fmac_f32_e32 v109, v170, v109
	v_div_scale_f32 v170, vcc, v104, v105, v104
	v_mul_f32_e32 v171, v170, v109
	v_fma_f32 v173, -v108, v171, v170
	v_fmac_f32_e32 v171, v173, v109
	v_fma_f32 v108, -v108, v171, v170
	v_div_fmas_f32 v108, v108, v109, v171
	v_div_fixup_f32 v173, v108, v105, v104
	v_cvt_f32_f16_e32 v104, v224
	v_mul_f32_e32 v105, 0xbfb8aa3b, v104
	v_exp_f32_e32 v105, v105
	s_nop 0
	v_add_f32_e32 v105, 1.0, v105
	v_div_scale_f32 v108, s[8:9], v105, v105, v104
	v_rcp_f32_e32 v109, v108
	s_nop 0
	v_fma_f32 v170, -v108, v109, 1.0
	v_fmac_f32_e32 v109, v170, v109
	v_div_scale_f32 v170, vcc, v104, v105, v104
	v_mul_f32_e32 v171, v170, v109
	v_fma_f32 v176, -v108, v171, v170
	v_fmac_f32_e32 v171, v176, v109
	v_fma_f32 v108, -v108, v171, v170
	v_div_fmas_f32 v108, v108, v109, v171
	v_div_fixup_f32 v176, v108, v105, v104
	v_cvt_f32_f16_e32 v104, v223
	v_mul_f32_e32 v105, 0xbfb8aa3b, v104
	v_exp_f32_e32 v105, v105
	s_nop 0
	v_add_f32_e32 v105, 1.0, v105
	v_div_scale_f32 v108, s[8:9], v105, v105, v104
	v_rcp_f32_e32 v109, v108
	s_nop 0
	v_fma_f32 v170, -v108, v109, 1.0
	v_fmac_f32_e32 v109, v170, v109
	v_div_scale_f32 v170, vcc, v104, v105, v104
	v_mul_f32_e32 v171, v170, v109
	v_fma_f32 v177, -v108, v171, v170
	v_fmac_f32_e32 v171, v177, v109
	v_fma_f32 v108, -v108, v171, v170
	v_div_fmas_f32 v108, v108, v109, v171
	v_div_fixup_f32 v177, v108, v105, v104
	v_mov_b32_e32 v104, v111
	v_mov_b32_e32 v105, v107
	v_pk_mul_f32 v[104:105], v[104:105], v[104:105]
	v_mov_b32_e32 v108, v103
	v_mov_b32_e32 v109, v99
	v_pk_mul_f32 v[108:109], v[108:109], v[108:109]
	v_mov_b32_e32 v170, v104
	v_mov_b32_e32 v171, v100
	v_mov_b32_e32 v100, v105
	v_pk_add_f32 v[100:101], v[170:171], v[100:101]
	v_mov_b32_e32 v104, v108
	v_mov_b32_e32 v105, v96
	v_pk_add_f32 v[100:101], v[100:101], v[104:105]
	v_mov_b32_e32 v96, v109
	v_pk_add_f32 v[96:97], v[100:101], v[96:97]
	s_nop 1
	v_mov_b32_dpp v101, v97 quad_perm:[1,0,3,2] row_mask:0xf bank_mask:0xf bound_ctrl:1
	v_mov_b32_dpp v100, v96 quad_perm:[1,0,3,2] row_mask:0xf bank_mask:0xf bound_ctrl:1
	v_pk_add_f32 v[96:97], v[96:97], v[100:101]
	s_nop 1
	v_mov_b32_dpp v101, v97 quad_perm:[2,3,0,1] row_mask:0xf bank_mask:0xf bound_ctrl:1
	v_mov_b32_dpp v100, v96 quad_perm:[2,3,0,1] row_mask:0xf bank_mask:0xf bound_ctrl:1
	v_pk_add_f32 v[96:97], v[96:97], v[100:101]
	s_nop 1
	v_mov_b32_dpp v101, v97 row_ror:4 row_mask:0xf bank_mask:0xf bound_ctrl:1
	v_mov_b32_dpp v100, v96 row_ror:4 row_mask:0xf bank_mask:0xf bound_ctrl:1
	v_pk_add_f32 v[96:97], v[96:97], v[100:101]
	s_nop 1
	v_mov_b32_dpp v101, v97 row_ror:8 row_mask:0xf bank_mask:0xf bound_ctrl:1
	v_mov_b32_dpp v100, v96 row_ror:8 row_mask:0xf bank_mask:0xf bound_ctrl:1
	v_pk_add_f32 v[96:97], v[96:97], v[100:101]
	s_nop 0
	v_pk_fma_f32 v[96:97], v[96:97], s[0:1], v[174:175] op_sel_hi:[1,0,0]
	s_nop 0
	v_mul_f32_e32 v100, 0x4b800000, v97
	v_cmp_gt_f32_e64 s[8:9], s49, v97
	v_cmp_gt_f32_e32 vcc, s49, v96
	s_nop 0
	v_cndmask_b32_e64 v97, v97, v100, s[8:9]
	v_rsq_f32_e32 v97, v97
	s_nop 0
	v_mul_f32_e32 v100, 0x45800000, v97
	v_cndmask_b32_e64 v97, v97, v100, s[8:9]
	v_mul_f32_e32 v100, v110, v97
	v_mul_f32_e32 v100, v234, v100
	v_mul_f32_e32 v100, v172, v100
	v_med3_f32 v100, v100, s57, v194
	v_cvt_f16_f32_e32 v100, v100
	global_store_short v[168:169], v100, off offset:768
	v_mul_f32_e32 v100, v106, v97
	v_mul_f32_e32 v100, v233, v100
	v_mul_f32_e32 v100, v173, v100
	v_med3_f32 v100, v100, s57, v194
	v_cvt_f16_f32_e32 v100, v100
	global_store_short v[168:169], v100, off offset:800
	v_mul_f32_e32 v100, v102, v97
	v_mul_f32_e32 v97, v98, v97
	v_mul_f32_e32 v97, v231, v97
	v_mul_f32_e32 v97, v177, v97
	v_med3_f32 v97, v97, s57, v194
	v_cvt_f16_f32_e32 v97, v97
	v_mul_f32_e32 v100, v232, v100
	v_mul_f32_e32 v100, v176, v100
	v_med3_f32 v100, v100, s57, v194
	global_store_short v[168:169], v97, off offset:864
	v_mul_f32_e32 v97, 0x4b800000, v96
	v_cndmask_b32_e32 v96, v96, v97, vcc
	v_rsq_f32_e32 v96, v96
	v_cvt_f16_f32_e32 v100, v100
	v_mul_f32_e32 v97, 0x45800000, v96
	v_cndmask_b32_e32 v96, v96, v97, vcc
	v_cvt_f32_f16_e32 v97, v181
	global_store_short v[168:169], v100, off offset:832
	v_mul_f32_e32 v98, v111, v96
	v_mul_f32_e32 v98, v234, v98
	v_mul_f32_e32 v100, 0xbfb8aa3b, v97
	v_exp_f32_e32 v100, v100
	s_nop 0
	v_add_f32_e32 v100, 1.0, v100
	v_div_scale_f32 v101, s[8:9], v100, v100, v97
	v_rcp_f32_e32 v102, v101
	s_nop 0
	v_fma_f32 v104, -v101, v102, 1.0
	v_fmac_f32_e32 v102, v104, v102
	v_div_scale_f32 v104, vcc, v97, v100, v97
	v_mul_f32_e32 v105, v104, v102
	v_fma_f32 v106, -v101, v105, v104
	v_fmac_f32_e32 v105, v106, v102
	v_fma_f32 v101, -v101, v105, v104
	v_div_fmas_f32 v101, v101, v102, v105
	v_div_fixup_f32 v97, v101, v100, v97
	v_mul_f32_e32 v97, v97, v98
	v_med3_f32 v97, v97, s57, v194
	v_cvt_f16_f32_e32 v97, v97
	v_mul_f32_e32 v98, v107, v96
	v_mul_f32_e32 v98, v233, v98
	global_store_short v[166:167], v97, off offset:3072
	v_cvt_f32_f16_e32 v97, v180
	v_mul_f32_e32 v100, 0xbfb8aa3b, v97
	v_exp_f32_e32 v100, v100
	s_nop 0
	v_add_f32_e32 v100, 1.0, v100
	v_div_scale_f32 v101, s[8:9], v100, v100, v97
	v_rcp_f32_e32 v102, v101
	s_nop 0
	v_fma_f32 v104, -v101, v102, 1.0
	v_fmac_f32_e32 v102, v104, v102
	v_div_scale_f32 v104, vcc, v97, v100, v97
	v_mul_f32_e32 v105, v104, v102
	v_fma_f32 v106, -v101, v105, v104
	v_fmac_f32_e32 v105, v106, v102
	v_fma_f32 v101, -v101, v105, v104
	v_div_fmas_f32 v101, v101, v102, v105
	v_div_fixup_f32 v97, v101, v100, v97
	v_mul_f32_e32 v97, v97, v98
	v_med3_f32 v97, v97, s57, v194
	v_cvt_f16_f32_e32 v97, v97
	v_mul_f32_e32 v98, v103, v96
	v_mul_f32_e32 v98, v232, v98
	v_mul_f32_e32 v96, v99, v96
	global_store_short v[166:167], v97, off offset:3104
	v_cvt_f32_f16_e32 v97, v179
	v_mul_f32_e32 v96, v231, v96
	v_mul_f32_e32 v100, 0xbfb8aa3b, v97
	v_exp_f32_e32 v100, v100
	s_nop 0
	v_add_f32_e32 v100, 1.0, v100
	v_div_scale_f32 v101, s[8:9], v100, v100, v97
	v_rcp_f32_e32 v102, v101
	s_nop 0
	v_fma_f32 v103, -v101, v102, 1.0
	v_fmac_f32_e32 v102, v103, v102
	v_div_scale_f32 v103, vcc, v97, v100, v97
	v_mul_f32_e32 v104, v103, v102
	v_fma_f32 v105, -v101, v104, v103
	v_fmac_f32_e32 v104, v105, v102
	v_fma_f32 v101, -v101, v104, v103
	v_div_fmas_f32 v101, v101, v102, v104
	v_div_fixup_f32 v97, v101, v100, v97
	v_mul_f32_e32 v97, v97, v98
	v_med3_f32 v97, v97, s57, v194
	v_cvt_f16_f32_e32 v97, v97
	global_store_short v[166:167], v97, off offset:3136
	v_cvt_f32_f16_e32 v97, v178
	v_mul_f32_e32 v98, 0xbfb8aa3b, v97
	v_exp_f32_e32 v98, v98
	s_nop 0
	v_add_f32_e32 v98, 1.0, v98
	v_div_scale_f32 v99, s[8:9], v98, v98, v97
	v_rcp_f32_e32 v100, v99
	s_nop 0
	v_fma_f32 v101, -v99, v100, 1.0
	v_fmac_f32_e32 v100, v101, v100
	v_div_scale_f32 v101, vcc, v97, v98, v97
	v_mul_f32_e32 v102, v101, v100
	v_fma_f32 v103, -v99, v102, v101
	v_fmac_f32_e32 v102, v103, v100
	v_fma_f32 v99, -v99, v102, v101
	v_div_fmas_f32 v99, v99, v100, v102
	v_div_fixup_f32 v97, v99, v98, v97
	v_mul_f32_e32 v96, v97, v96
	v_med3_f32 v96, v96, s57, v194
	v_cvt_f16_f32_e32 v96, v96
	s_andn2_b64 vcc, exec, s[10:11]
	global_store_short v[166:167], v96, off offset:3168
	ds_read_b128 v[96:99], v116 offset:55296
	ds_read_b128 v[240:243], v117 offset:36864
	ds_read_b128 v[244:247], v117 offset:39168
	ds_read_b128 v[252:255], v117 offset:41472
	s_waitcnt lgkmcnt(2)
	v_mul_f32_e64 v82, v82, v112
	v_mul_f32_e64 v83, v83, v112
	v_pk_mul_f32 v[80:81], v[80:81], v[112:113] op_sel_hi:[1,0]
	v_pk_mul_f32 v[86:87], v[86:87], v[112:113] op_sel_hi:[1,0]
	v_mul_f32_e64 v84, v84, v112
	v_mul_f32_e64 v85, v85, v112
	v_pk_mul_f32 v[90:91], v[90:91], v[112:113] op_sel_hi:[1,0]
	v_pk_mul_f32 v[88:89], v[88:89], v[112:113] op_sel_hi:[1,0]
	v_pk_mul_f32 v[94:95], v[94:95], v[112:113] op_sel_hi:[1,0]
	v_pk_mul_f32 v[92:93], v[92:93], v[112:113] op_sel_hi:[1,0]
	s_nop 1
	v_mfma_f32_16x16x32_f16 v[80:83], v[96:99], v[240:243], v[80:83]
	ds_read_b128 v[240:243], v117 offset:43776
	ds_read_b128 v[100:103], v116 offset:55360
	s_waitcnt lgkmcnt(3)
	v_mfma_f32_16x16x32_f16 v[84:87], v[96:99], v[244:247], v[84:87]
	ds_read_b128 v[244:247], v117 offset:36928
	s_waitcnt lgkmcnt(3)
	v_mfma_f32_16x16x32_f16 v[88:91], v[96:99], v[252:255], v[88:91]
	ds_read_b128 v[252:255], v117 offset:39232
	s_waitcnt lgkmcnt(3)
	v_mfma_f32_16x16x32_f16 v[92:95], v[96:99], v[240:243], v[92:95]
	ds_read_b128 v[240:243], v117 offset:41536
	s_waitcnt lgkmcnt(2)
	v_mfma_f32_16x16x32_f16 v[80:83], v[100:103], v[244:247], v[80:83]
	ds_read_b128 v[244:247], v117 offset:43840
	s_waitcnt lgkmcnt(2)
	v_mfma_f32_16x16x32_f16 v[84:87], v[100:103], v[252:255], v[84:87]
	s_waitcnt lgkmcnt(1)
	v_mfma_f32_16x16x32_f16 v[88:91], v[100:103], v[240:243], v[88:91]
	s_waitcnt lgkmcnt(0)
	s_barrier
	v_mfma_f32_16x16x32_f16 v[92:95], v[100:103], v[244:247], v[92:95]
	v_max_f32_e32 v96, v80, v80
	v_med3_f32 v96, v96, s57, v194
	v_cvt_f16_f32_e32 v96, v96
	ds_write_b16 v215, v96 offset:46080
	v_max_f32_e32 v96, v81, v81
	v_med3_f32 v96, v96, s57, v194
	v_cvt_f16_f32_e32 v96, v96
	ds_write_b16 v215, v96 offset:46224
	v_max_f32_e32 v96, v82, v82
	v_med3_f32 v96, v96, s57, v194
	v_cvt_f16_f32_e32 v96, v96
	ds_write_b16 v215, v96 offset:46368
	v_max_f32_e32 v96, v83, v83
	v_med3_f32 v96, v96, s57, v194
	v_cvt_f16_f32_e32 v96, v96
	ds_write_b16 v215, v96 offset:46512
	v_max_f32_e32 v96, v84, v84
	v_med3_f32 v96, v96, s57, v194
	v_cvt_f16_f32_e32 v96, v96
	ds_write_b16 v215, v96 offset:46112
	v_max_f32_e32 v96, v85, v85
	v_med3_f32 v96, v96, s57, v194
	v_cvt_f16_f32_e32 v96, v96
	ds_write_b16 v216, v96 offset:46224
	v_max_f32_e32 v96, v86, v86
	v_med3_f32 v96, v96, s57, v194
	v_cvt_f16_f32_e32 v96, v96
	ds_write_b16 v216, v96 offset:46368
	v_max_f32_e32 v96, v87, v87
	v_med3_f32 v96, v96, s57, v194
	v_cvt_f16_f32_e32 v96, v96
	ds_write_b16 v216, v96 offset:46512
	v_max_f32_e32 v96, v88, v88
	v_med3_f32 v96, v96, s57, v194
	v_cvt_f16_f32_e32 v96, v96
	ds_write_b16 v215, v96 offset:46144
	v_max_f32_e32 v96, v89, v89
	v_med3_f32 v96, v96, s57, v194
	v_cvt_f16_f32_e32 v96, v96
	ds_write_b16 v217, v96 offset:46224
	v_max_f32_e32 v96, v90, v90
	v_med3_f32 v96, v96, s57, v194
	v_cvt_f16_f32_e32 v96, v96
	ds_write_b16 v217, v96 offset:46368
	v_max_f32_e32 v96, v91, v91
	v_med3_f32 v96, v96, s57, v194
	v_cvt_f16_f32_e32 v96, v96
	ds_write_b16 v217, v96 offset:46512
	v_max_f32_e32 v96, v92, v92
	v_med3_f32 v96, v96, s57, v194
	v_cvt_f16_f32_e32 v96, v96
	ds_write_b16 v215, v96 offset:46176
	v_max_f32_e32 v96, v93, v93
	v_med3_f32 v96, v96, s57, v194
	v_cvt_f16_f32_e32 v96, v96
	ds_write_b16 v218, v96 offset:46224
	v_max_f32_e32 v96, v94, v94
	v_med3_f32 v96, v96, s57, v194
	v_cvt_f16_f32_e32 v96, v96
	ds_write_b16 v218, v96 offset:46368
	v_max_f32_e32 v96, v95, v95
	v_med3_f32 v96, v96, s57, v194
	v_cvt_f16_f32_e32 v96, v96
	ds_write_b16 v218, v96 offset:46512
	ds_write_b128 v220, v[16:19]
	ds_write_b128 v211, v[20:23]
	ds_write_b128 v221, v[24:27]
	ds_write_b128 v212, v[28:31]
	ds_write_b128 v222, v[32:35]
	ds_write_b128 v213, v[36:39]
	s_waitcnt lgkmcnt(0)
.LBB0_525:
	v_lshl_add_u64 v[108:109], v[142:143], 0, v[140:141]
	v_add_co_u32_e32 v96, vcc, 0x65000, v108
	global_load_dword v112, v192, s[12:13] offset:4 sc1
	s_nop 0
	v_addc_co_u32_e32 v97, vcc, 0, v109, vcc
	global_load_ushort v238, v[96:97], off offset:256
	global_load_ushort v237, v[96:97], off offset:288
	global_load_ushort v236, v[96:97], off offset:320
	global_load_ushort v235, v[96:97], off offset:352
	v_add_co_u32_e32 v96, vcc, 0x66000, v108
	s_cmpk_lt_u32 s14, 0x7f
	s_nop 0
	v_addc_co_u32_e32 v97, vcc, 0, v109, vcc
	global_load_ushort v234, v[96:97], off offset:2560
	global_load_ushort v233, v[96:97], off offset:2592
	global_load_ushort v232, v[96:97], off offset:2624
	global_load_ushort v231, v[96:97], off offset:2656
	v_add_co_u32_e32 v96, vcc, 0x68000, v108
	s_cselect_b64 s[10:11], -1, 0
	s_nop 0
	v_addc_co_u32_e32 v97, vcc, 0, v109, vcc
	global_load_ushort v230, v[96:97], off offset:768
	global_load_ushort v229, v[96:97], off offset:800
	global_load_ushort v228, v[96:97], off offset:832
	global_load_ushort v227, v[96:97], off offset:864
	v_add_co_u32_e32 v96, vcc, 0x69000, v108
	s_cmpk_gt_u32 s14, 0x7e
	s_nop 0
	v_addc_co_u32_e32 v97, vcc, 0, v109, vcc
	global_load_ushort v226, v[96:97], off offset:3072
	global_load_ushort v225, v[96:97], off offset:3104
	global_load_ushort v224, v[96:97], off offset:3136
	global_load_ushort v223, v[96:97], off offset:3168
	s_cmpk_lt_u32 s15, 0x7e
	s_cbranch_scc0 .Lscan_pfB_skip
	v_add_co_u32_e32 v0, vcc, 0xc81e000, v164
	s_nop 1
	v_addc_co_u32_e32 v1, vcc, 0, v165, vcc
	v_add_co_u32_e32 v4, vcc, 0xc81e000, v162
	s_nop 1
	v_addc_co_u32_e32 v5, vcc, 0, v163, vcc
	v_add_co_u32_e32 v8, vcc, 0xc81e000, v160
	global_load_dwordx4 v[0:3], v[0:1], off
	s_nop 0
	global_load_dwordx4 v[4:7], v[4:5], off
	v_addc_co_u32_e32 v9, vcc, 0, v161, vcc
	v_add_co_u32_e32 v12, vcc, 0xc81e000, v158
	s_nop 1
	v_addc_co_u32_e32 v13, vcc, 0, v159, vcc
	v_add_co_u32_e32 v16, vcc, 0xc81e000, v156
	global_load_dwordx4 v[8:11], v[8:9], off
	s_nop 0
	global_load_dwordx4 v[12:15], v[12:13], off
	v_addc_co_u32_e32 v17, vcc, 0, v157, vcc
	v_add_co_u32_e32 v20, vcc, 0xc81e000, v154
	s_nop 1
	v_addc_co_u32_e32 v21, vcc, 0, v155, vcc
	v_add_co_u32_e32 v24, vcc, 0xc81e000, v152
	global_load_dwordx4 v[16:19], v[16:17], off
	s_nop 0
	global_load_dwordx4 v[20:23], v[20:21], off
	v_addc_co_u32_e32 v25, vcc, 0, v153, vcc
	v_add_co_u32_e32 v28, vcc, 0xc81e000, v150
	s_nop 1
	v_addc_co_u32_e32 v29, vcc, 0, v151, vcc
	v_add_co_u32_e32 v32, vcc, 0xc81e000, v148
	global_load_dwordx4 v[24:27], v[24:25], off
	s_nop 0
	global_load_dwordx4 v[28:31], v[28:29], off
	v_addc_co_u32_e32 v33, vcc, 0, v149, vcc
	v_add_co_u32_e32 v36, vcc, 0xc81e000, v146
	s_nop 1
	v_addc_co_u32_e32 v37, vcc, 0, v147, vcc
	global_load_dwordx4 v[32:35], v[32:33], off
	s_nop 0
	global_load_dwordx4 v[36:39], v[36:37], off
.Lscan_pfB_skip:
	s_cmpk_gt_u32 s14, 0x7e
	ds_read_b64 v[110:111], v214 offset:9216
	ds_read_b128 v[146:149], v116 offset:46080
	ds_read_b128 v[240:243], v117
	ds_read_b128 v[244:247], v117 offset:2304
	ds_read_b128 v[252:255], v117 offset:4608
	s_waitcnt lgkmcnt(2)
	v_mfma_f32_16x16x32_f16 v[154:157], v[146:149], v[240:243], 0
	ds_read_b128 v[240:243], v117 offset:6912
	ds_read_b128 v[150:153], v116 offset:46144
	s_waitcnt lgkmcnt(3)
	v_mfma_f32_16x16x32_f16 v[104:107], v[146:149], v[244:247], 0
	ds_read_b128 v[244:247], v117 offset:64
	s_waitcnt lgkmcnt(3)
	v_mfma_f32_16x16x32_f16 v[100:103], v[146:149], v[252:255], 0
	ds_read_b128 v[252:255], v117 offset:2368
	s_waitcnt lgkmcnt(3)
	v_mfma_f32_16x16x32_f16 v[96:99], v[146:149], v[240:243], 0
	ds_read_b128 v[240:243], v117 offset:4672
	s_waitcnt lgkmcnt(2)
	v_mfma_f32_16x16x32_f16 v[154:157], v[150:153], v[244:247], v[154:157]
	ds_read_b128 v[244:247], v117 offset:6976
	s_waitcnt lgkmcnt(2)
	v_mfma_f32_16x16x32_f16 v[104:107], v[150:153], v[252:255], v[104:107]
	s_waitcnt lgkmcnt(1)
	v_mfma_f32_16x16x32_f16 v[100:103], v[150:153], v[240:243], v[100:103]
	s_waitcnt lgkmcnt(0)
	v_mfma_f32_16x16x32_f16 v[96:99], v[150:153], v[244:247], v[96:99]
	v_cvt_f32_f16_e32 v146, v110
	v_cvt_f32_f16_sdwa v110, v110 dst_sel:DWORD dst_unused:UNUSED_PAD src0_sel:WORD_1
	v_sub_f32_e32 v146, v146, v154
	v_sub_f32_e32 v110, v110, v155
	v_med3_f32 v110, v110, s57, v194
	v_cvt_f16_f32_e32 v110, v110
	v_med3_f32 v146, v146, s57, v194
	v_cvt_f16_f32_e32 v146, v146
	ds_write_b16 v215, v110 offset:55440
	v_cvt_f32_f16_e32 v110, v111
	ds_write_b16 v215, v146 offset:55296
	v_sub_f32_e32 v110, v110, v156
	v_med3_f32 v110, v110, s57, v194
	v_cvt_f16_f32_e32 v110, v110
	ds_write_b16 v215, v110 offset:55584
	v_cvt_f32_f16_sdwa v110, v111 dst_sel:DWORD dst_unused:UNUSED_PAD src0_sel:WORD_1
	v_sub_f32_e32 v110, v110, v157
	v_med3_f32 v110, v110, s57, v194
	v_cvt_f16_f32_e32 v110, v110
	ds_write_b16 v215, v110 offset:55728
	ds_read_b64 v[110:111], v214 offset:11520
	s_waitcnt lgkmcnt(0)
	v_cvt_f32_f16_e32 v146, v110
	v_sub_f32_e32 v104, v146, v104
	v_med3_f32 v104, v104, s57, v194
	v_cvt_f16_f32_e32 v104, v104
	ds_write_b16 v215, v104 offset:55328
	v_cvt_f32_f16_sdwa v104, v110 dst_sel:DWORD dst_unused:UNUSED_PAD src0_sel:WORD_1
	v_sub_f32_e32 v104, v104, v105
	v_med3_f32 v104, v104, s57, v194
	v_cvt_f16_f32_e32 v104, v104
	ds_write_b16 v216, v104 offset:55440
	v_cvt_f32_f16_e32 v104, v111
	v_sub_f32_e32 v104, v104, v106
	v_med3_f32 v104, v104, s57, v194
	v_cvt_f16_f32_e32 v104, v104
	ds_write_b16 v216, v104 offset:55584
	v_cvt_f32_f16_sdwa v104, v111 dst_sel:DWORD dst_unused:UNUSED_PAD src0_sel:WORD_1
	v_sub_f32_e32 v104, v104, v107
	v_med3_f32 v104, v104, s57, v194
	v_cvt_f16_f32_e32 v104, v104
	ds_write_b16 v216, v104 offset:55728
	ds_read_b64 v[104:105], v214 offset:13824
	s_waitcnt lgkmcnt(0)
	v_cvt_f32_f16_e32 v106, v104
	v_sub_f32_e32 v100, v106, v100
	v_med3_f32 v100, v100, s57, v194
	v_cvt_f16_f32_e32 v100, v100
	ds_write_b16 v215, v100 offset:55360
	v_cvt_f32_f16_sdwa v100, v104 dst_sel:DWORD dst_unused:UNUSED_PAD src0_sel:WORD_1
	v_sub_f32_e32 v100, v100, v101
	v_med3_f32 v100, v100, s57, v194
	v_cvt_f16_f32_e32 v100, v100
	ds_write_b16 v217, v100 offset:55440
	v_cvt_f32_f16_e32 v100, v105
	v_sub_f32_e32 v100, v100, v102
	v_med3_f32 v100, v100, s57, v194
	v_cvt_f16_f32_e32 v100, v100
	ds_write_b16 v217, v100 offset:55584
	v_cvt_f32_f16_sdwa v100, v105 dst_sel:DWORD dst_unused:UNUSED_PAD src0_sel:WORD_1
	v_sub_f32_e32 v100, v100, v103
	v_med3_f32 v100, v100, s57, v194
	v_cvt_f16_f32_e32 v100, v100
	ds_write_b16 v217, v100 offset:55728
	ds_read_b64 v[100:101], v214 offset:16128
	s_waitcnt lgkmcnt(0)
	v_cvt_f32_f16_e32 v102, v100
	v_sub_f32_e32 v96, v102, v96
	v_med3_f32 v96, v96, s57, v194
	v_cvt_f16_f32_e32 v96, v96
	ds_write_b16 v215, v96 offset:55392
	v_cvt_f32_f16_sdwa v96, v100 dst_sel:DWORD dst_unused:UNUSED_PAD src0_sel:WORD_1
	v_sub_f32_e32 v96, v96, v97
	v_med3_f32 v96, v96, s57, v194
	v_cvt_f16_f32_e32 v96, v96
	ds_write_b16 v218, v96 offset:55440
	v_cvt_f32_f16_e32 v96, v101
	v_sub_f32_e32 v96, v96, v98
	v_med3_f32 v96, v96, s57, v194
	v_cvt_f16_f32_e32 v96, v96
	ds_write_b16 v218, v96 offset:55584
	v_cvt_f32_f16_sdwa v96, v101 dst_sel:DWORD dst_unused:UNUSED_PAD src0_sel:WORD_1
	v_sub_f32_e32 v96, v96, v99
	v_med3_f32 v96, v96, s57, v194
	v_cvt_f16_f32_e32 v96, v96
	ds_write_b16 v218, v96 offset:55728
	s_waitcnt lgkmcnt(0)
	s_barrier
	s_cbranch_scc1 .LBB0_527
	ds_write_b128 v115, v[40:43]
	ds_write_b128 v209, v[44:47]
	ds_write_b128 v219, v[48:51]
	ds_write_b128 v210, v[52:55]
.LBB0_527:
	s_mov_b64 s[8:9], 0x65100
	v_lshl_add_u64 v[178:179], v[108:109], 0, s[8:9]
	s_mov_b64 s[8:9], 0x65120
	v_lshl_add_u64 v[176:177], v[108:109], 0, s[8:9]
	s_mov_b64 s[8:9], 0x65140
	v_lshl_add_u64 v[174:175], v[108:109], 0, s[8:9]
	s_mov_b64 s[8:9], 0x65160
	v_lshl_add_u64 v[172:173], v[108:109], 0, s[8:9]
	s_mov_b64 s[8:9], 0x66a00
	v_lshl_add_u64 v[168:169], v[108:109], 0, s[8:9]
	s_mov_b64 s[8:9], 0x66a20
	v_lshl_add_u64 v[166:167], v[108:109], 0, s[8:9]
	s_mov_b64 s[8:9], 0x66a40
	v_lshl_add_u64 v[164:165], v[108:109], 0, s[8:9]
	s_mov_b64 s[8:9], 0x66a60
	v_lshl_add_u64 v[162:163], v[108:109], 0, s[8:9]
	s_mov_b64 s[8:9], 0x68300
	v_lshl_add_u64 v[160:161], v[108:109], 0, s[8:9]
	s_mov_b64 s[8:9], 0x68320
	v_lshl_add_u64 v[158:159], v[108:109], 0, s[8:9]
	s_mov_b64 s[8:9], 0x68340
	v_lshl_add_u64 v[156:157], v[108:109], 0, s[8:9]
	s_mov_b64 s[8:9], 0x68360
	v_lshl_add_u64 v[154:155], v[108:109], 0, s[8:9]
	s_mov_b64 s[8:9], 0x69c00
	v_lshl_add_u64 v[152:153], v[108:109], 0, s[8:9]
	s_mov_b64 s[8:9], 0x69c20
	v_lshl_add_u64 v[150:151], v[108:109], 0, s[8:9]
	s_mov_b64 s[8:9], 0x69c40
	v_lshl_add_u64 v[148:149], v[108:109], 0, s[8:9]
	s_mov_b64 s[8:9], 0x69c60
	v_lshl_add_u64 v[146:147], v[108:109], 0, s[8:9]
	s_waitcnt vmcnt(15)
	v_cvt_f32_f16_e32 v239, v238
	s_mov_b32 s0, 0x358637bd
	global_load_dword v238, v[118:119], off
	ds_read_b128 v[240:243], v116 offset:27648
	ds_read_b128 v[244:247], v117 offset:46080
	ds_read_b128 v[252:255], v117 offset:48384
	s_waitcnt lgkmcnt(1)
	v_mfma_f32_16x16x32_f16 v[108:111], v[240:243], v[244:247], 0
	ds_read_b128 v[244:247], v117 offset:50688
	s_waitcnt lgkmcnt(1)
	v_mfma_f32_16x16x32_f16 v[104:107], v[240:243], v[252:255], 0
	ds_read_b128 v[252:255], v117 offset:52992
	s_waitcnt lgkmcnt(1)
	v_mfma_f32_16x16x32_f16 v[100:103], v[240:243], v[244:247], 0
	s_waitcnt lgkmcnt(0)
	v_mfma_f32_16x16x32_f16 v[96:99], v[240:243], v[252:255], 0
	ds_read_b128 v[240:243], v116 offset:27712
	ds_read_b128 v[244:247], v117 offset:46144
	ds_read_b128 v[252:255], v117 offset:48448
	s_waitcnt lgkmcnt(1)
	v_mfma_f32_16x16x32_f16 v[108:111], v[240:243], v[244:247], v[108:111]
	ds_read_b128 v[244:247], v117 offset:50752
	s_waitcnt lgkmcnt(1)
	v_mfma_f32_16x16x32_f16 v[104:107], v[240:243], v[252:255], v[104:107]
	ds_read_b128 v[252:255], v117 offset:53056
	s_waitcnt lgkmcnt(1)
	v_mfma_f32_16x16x32_f16 v[100:103], v[240:243], v[244:247], v[100:103]
	s_waitcnt lgkmcnt(0)
	v_mfma_f32_16x16x32_f16 v[96:99], v[240:243], v[252:255], v[96:99]
	ds_read_b128 v[240:243], v116 offset:18432
	ds_read_b128 v[244:247], v117 offset:55296
	ds_read_b128 v[252:255], v117 offset:57600
	s_waitcnt lgkmcnt(1)
	v_mfma_f32_16x16x32_f16 v[108:111], v[240:243], v[244:247], v[108:111]
	ds_read_b128 v[244:247], v117 offset:59904
	s_waitcnt lgkmcnt(1)
	v_mfma_f32_16x16x32_f16 v[104:107], v[240:243], v[252:255], v[104:107]
	ds_read_b128 v[252:255], v117 offset:62208
	s_waitcnt lgkmcnt(1)
	v_mfma_f32_16x16x32_f16 v[100:103], v[240:243], v[244:247], v[100:103]
	s_waitcnt lgkmcnt(0)
	v_mfma_f32_16x16x32_f16 v[96:99], v[240:243], v[252:255], v[96:99]
	ds_read_b128 v[240:243], v116 offset:18496
	ds_read_b128 v[244:247], v117 offset:55360
	ds_read_b128 v[252:255], v117 offset:57664
	s_waitcnt lgkmcnt(1)
	v_mfma_f32_16x16x32_f16 v[108:111], v[240:243], v[244:247], v[108:111]
	ds_read_b128 v[244:247], v117 offset:59968
	s_waitcnt lgkmcnt(1)
	v_mfma_f32_16x16x32_f16 v[104:107], v[240:243], v[252:255], v[104:107]
	s_nop 7
	v_mov_b32_e32 v170, v108
	v_mov_b32_e32 v171, v104
	ds_read_b128 v[252:255], v117 offset:62272
	s_waitcnt lgkmcnt(1)
	v_mfma_f32_16x16x32_f16 v[100:103], v[240:243], v[244:247], v[100:103]
	s_nop 7
	v_mul_f32_e64 v180, v170, v170
	v_mul_f32_e64 v181, v171, v171
	s_waitcnt lgkmcnt(0)
	v_mfma_f32_16x16x32_f16 v[96:99], v[240:243], v[252:255], v[96:99]
	v_mul_f32_e32 v240, 0xbfb8aa3b, v239
	v_exp_f32_e32 v240, v240
	v_mov_b32_e32 v170, v100
	s_nop 4
	v_mov_b32_e32 v171, v96
	v_pk_mul_f32 v[170:171], v[170:171], v[170:171]
	v_add_f32_e32 v240, 1.0, v240
	v_div_scale_f32 v241, s[8:9], v240, v240, v239
	v_rcp_f32_e32 v242, v241
	s_nop 0
	v_fma_f32 v243, -v241, v242, 1.0
	v_fmac_f32_e32 v242, v243, v242
	v_div_scale_f32 v243, vcc, v239, v240, v239
	v_mul_f32_e32 v244, v243, v242
	v_fma_f32 v245, -v241, v244, v243
	v_fmac_f32_e32 v244, v245, v242
	v_fma_f32 v241, -v241, v244, v243
	v_div_fmas_f32 v241, v241, v242, v244
	v_div_fixup_f32 v239, v241, v240, v239
	s_waitcnt vmcnt(15)
	v_cvt_f32_f16_e32 v240, v237
	global_load_dword v237, v[118:119], off offset:64
	v_mul_f32_e32 v241, 0xbfb8aa3b, v240
	v_exp_f32_e32 v241, v241
	s_nop 0
	v_add_f32_e32 v241, 1.0, v241
	v_div_scale_f32 v242, s[8:9], v241, v241, v240
	v_rcp_f32_e32 v243, v242
	s_nop 0
	v_fma_f32 v244, -v242, v243, 1.0
	v_fmac_f32_e32 v243, v244, v243
	v_div_scale_f32 v244, vcc, v240, v241, v240
	v_mul_f32_e32 v245, v244, v243
	v_fma_f32 v246, -v242, v245, v244
	v_fmac_f32_e32 v245, v246, v243
	v_fma_f32 v242, -v242, v245, v244
	v_div_fmas_f32 v242, v242, v243, v245
	v_div_fixup_f32 v246, v242, v241, v240
	s_waitcnt vmcnt(15)
	v_cvt_f32_f16_e32 v240, v236
	global_load_dword v236, v[118:119], off offset:128
	v_mul_f32_e32 v241, 0xbfb8aa3b, v240
	v_exp_f32_e32 v241, v241
	s_nop 0
	v_add_f32_e32 v241, 1.0, v241
	v_div_scale_f32 v242, s[8:9], v241, v241, v240
	v_rcp_f32_e32 v243, v242
	s_nop 0
	v_fma_f32 v244, -v242, v243, 1.0
	v_fmac_f32_e32 v243, v244, v243
	v_div_scale_f32 v244, vcc, v240, v241, v240
	v_mul_f32_e32 v245, v244, v243
	v_fma_f32 v247, -v242, v245, v244
	v_fmac_f32_e32 v245, v247, v243
	v_fma_f32 v242, -v242, v245, v244
	v_div_fmas_f32 v242, v242, v243, v245
	v_div_fixup_f32 v247, v242, v241, v240
	s_waitcnt vmcnt(15)
	v_cvt_f32_f16_e32 v240, v235
	global_load_dword v235, v[118:119], off offset:192
	v_mul_f32_e32 v241, 0xbfb8aa3b, v240
	v_exp_f32_e32 v241, v241
	s_nop 0
	v_add_f32_e32 v241, 1.0, v241
	v_div_scale_f32 v242, s[8:9], v241, v241, v240
	v_rcp_f32_e32 v243, v242
	s_nop 0
	v_fma_f32 v244, -v242, v243, 1.0
	v_fmac_f32_e32 v243, v244, v243
	v_div_scale_f32 v244, vcc, v240, v241, v240
	v_mul_f32_e32 v245, v244, v243
	v_fma_f32 v248, -v242, v245, v244
	v_fmac_f32_e32 v245, v248, v243
	v_fma_f32 v242, -v242, v245, v244
	v_div_fmas_f32 v242, v242, v243, v245
	v_div_fixup_f32 v248, v242, v241, v240
	v_mov_b32_e32 v240, v109
	v_mov_b32_e32 v241, v105
	v_pk_mul_f32 v[240:241], v[240:241], v[240:241]
	v_mov_b32_e32 v242, v101
	v_mov_b32_e32 v243, v97
	v_pk_mul_f32 v[242:243], v[242:243], v[242:243]
	v_mov_b32_e32 v244, v240
	v_mov_b32_e32 v245, v180
	v_mov_b32_e32 v180, v241
	v_pk_add_f32 v[180:181], v[244:245], v[180:181]
	v_mov_b32_e32 v240, v242
	v_mov_b32_e32 v241, v170
	v_pk_add_f32 v[180:181], v[180:181], v[240:241]
	v_mov_b32_e32 v170, v243
	v_pk_add_f32 v[170:171], v[180:181], v[170:171]
	s_nop 1
	v_mov_b32_dpp v181, v171 quad_perm:[1,0,3,2] row_mask:0xf bank_mask:0xf bound_ctrl:1
	v_mov_b32_dpp v180, v170 quad_perm:[1,0,3,2] row_mask:0xf bank_mask:0xf bound_ctrl:1
	v_pk_add_f32 v[170:171], v[170:171], v[180:181]
	s_nop 1
	v_mov_b32_dpp v181, v171 quad_perm:[2,3,0,1] row_mask:0xf bank_mask:0xf bound_ctrl:1
	v_mov_b32_dpp v180, v170 quad_perm:[2,3,0,1] row_mask:0xf bank_mask:0xf bound_ctrl:1
	v_pk_add_f32 v[170:171], v[170:171], v[180:181]
	s_nop 1
	v_mov_b32_dpp v181, v171 row_ror:4 row_mask:0xf bank_mask:0xf bound_ctrl:1
	v_mov_b32_dpp v180, v170 row_ror:4 row_mask:0xf bank_mask:0xf bound_ctrl:1
	v_pk_add_f32 v[170:171], v[170:171], v[180:181]
	s_nop 1
	v_mov_b32_dpp v181, v171 row_ror:8 row_mask:0xf bank_mask:0xf bound_ctrl:1
	v_mov_b32_dpp v180, v170 row_ror:8 row_mask:0xf bank_mask:0xf bound_ctrl:1
	v_pk_add_f32 v[180:181], v[170:171], v[180:181]
	v_mov_b64_e32 v[170:171], s[0:1]
	s_mov_b32 s0, 0x3c800000
	v_pk_fma_f32 v[180:181], v[180:181], s[0:1], v[170:171] op_sel_hi:[1,0,0]
	s_nop 0
	v_mul_f32_e32 v240, 0x4b800000, v181
	v_cmp_gt_f32_e64 s[8:9], s49, v181
	v_cmp_gt_f32_e32 vcc, s49, v180
	s_nop 0
	v_cndmask_b32_e64 v181, v181, v240, s[8:9]
	v_rsq_f32_e32 v181, v181
	s_nop 0
	v_mul_f32_e32 v240, 0x45800000, v181
	v_cndmask_b32_e64 v181, v181, v240, s[8:9]
	v_mul_f32_e32 v96, v96, v181
	v_mul_f32_e32 v100, v100, v181
	s_waitcnt vmcnt(1)
	v_mul_f32_e32 v100, v236, v100
	v_mul_f32_e32 v100, v247, v100
	v_med3_f32 v100, v100, s57, v194
	s_waitcnt vmcnt(0)
	v_mul_f32_e32 v96, v235, v96
	v_mul_f32_e32 v96, v248, v96
	v_med3_f32 v96, v96, s57, v194
	v_cvt_f16_f32_e32 v96, v96
	v_cvt_f16_f32_e32 v100, v100
	v_mul_f32_e32 v108, v108, v181
	v_mul_f32_e32 v108, v238, v108
	global_store_short v[172:173], v96, off
	v_mul_f32_e32 v96, 0x4b800000, v180
	v_cndmask_b32_e32 v96, v180, v96, vcc
	v_rsq_f32_e32 v96, v96
	v_mul_f32_e32 v108, v239, v108
	v_med3_f32 v108, v108, s57, v194
	global_store_short v[174:175], v100, off
	v_mul_f32_e32 v100, 0x45800000, v96
	v_cvt_f16_f32_e32 v108, v108
	v_cndmask_b32_e32 v96, v96, v100, vcc
	v_cvt_f32_f16_e32 v100, v234
	v_mul_f32_e32 v104, v104, v181
	v_mul_f32_e32 v104, v237, v104
	global_store_short v[178:179], v108, off
	v_mul_f32_e32 v104, v246, v104
	v_mul_f32_e32 v108, 0xbfb8aa3b, v100
	v_med3_f32 v104, v104, s57, v194
	v_exp_f32_e32 v108, v108
	v_cvt_f16_f32_e32 v104, v104
	v_mul_f32_e32 v101, v101, v96
	v_mul_f32_e32 v101, v236, v101
	v_add_f32_e32 v108, 1.0, v108
	global_store_short v[176:177], v104, off
	v_mul_f32_e32 v104, v109, v96
	v_div_scale_f32 v109, s[8:9], v108, v108, v100
	v_rcp_f32_e32 v172, v109
	v_mul_f32_e32 v104, v238, v104
	v_fma_f32 v173, -v109, v172, 1.0
	v_fmac_f32_e32 v172, v173, v172
	v_div_scale_f32 v173, vcc, v100, v108, v100
	v_mul_f32_e32 v174, v173, v172
	v_fma_f32 v175, -v109, v174, v173
	v_fmac_f32_e32 v174, v175, v172
	v_fma_f32 v109, -v109, v174, v173
	v_div_fmas_f32 v109, v109, v172, v174
	v_div_fixup_f32 v100, v109, v108, v100
	v_mul_f32_e32 v100, v100, v104
	v_med3_f32 v100, v100, s57, v194
	v_cvt_f16_f32_e32 v100, v100
	v_mul_f32_e32 v104, v105, v96
	v_mul_f32_e32 v104, v237, v104
	v_mul_f32_e32 v96, v97, v96
	global_store_short v[168:169], v100, off
	v_cvt_f32_f16_e32 v100, v233
	v_mul_f32_e32 v96, v235, v96
	v_mul_f32_e32 v105, 0xbfb8aa3b, v100
	v_exp_f32_e32 v105, v105
	s_nop 0
	v_add_f32_e32 v105, 1.0, v105
	v_div_scale_f32 v108, s[8:9], v105, v105, v100
	v_rcp_f32_e32 v109, v108
	s_nop 0
	v_fma_f32 v168, -v108, v109, 1.0
	v_fmac_f32_e32 v109, v168, v109
	v_div_scale_f32 v168, vcc, v100, v105, v100
	v_mul_f32_e32 v169, v168, v109
	v_fma_f32 v172, -v108, v169, v168
	v_fmac_f32_e32 v169, v172, v109
	v_fma_f32 v108, -v108, v169, v168
	v_div_fmas_f32 v108, v108, v109, v169
	v_div_fixup_f32 v100, v108, v105, v100
	v_mul_f32_e32 v100, v100, v104
	v_med3_f32 v100, v100, s57, v194
	v_cvt_f16_f32_e32 v100, v100
	global_store_short v[166:167], v100, off
	v_cvt_f32_f16_e32 v100, v232
	v_mul_f32_e32 v104, 0xbfb8aa3b, v100
	v_exp_f32_e32 v104, v104
	s_nop 0
	v_add_f32_e32 v104, 1.0, v104
	v_div_scale_f32 v105, s[8:9], v104, v104, v100
	v_rcp_f32_e32 v108, v105
	s_nop 0
	v_fma_f32 v109, -v105, v108, 1.0
	v_fmac_f32_e32 v108, v109, v108
	v_div_scale_f32 v109, vcc, v100, v104, v100
	v_mul_f32_e32 v166, v109, v108
	v_fma_f32 v167, -v105, v166, v109
	v_fmac_f32_e32 v166, v167, v108
	v_fma_f32 v105, -v105, v166, v109
	v_div_fmas_f32 v105, v105, v108, v166
	v_div_fixup_f32 v100, v105, v104, v100
	v_mul_f32_e32 v100, v100, v101
	v_med3_f32 v100, v100, s57, v194
	v_cvt_f16_f32_e32 v100, v100
	global_store_short v[164:165], v100, off
	v_cvt_f32_f16_e32 v100, v231
	v_mul_f32_e32 v97, 0xbfb8aa3b, v100
	v_exp_f32_e32 v97, v97
	s_nop 0
	v_add_f32_e32 v97, 1.0, v97
	v_div_scale_f32 v101, s[8:9], v97, v97, v100
	v_rcp_f32_e32 v104, v101
	s_nop 0
	v_fma_f32 v105, -v101, v104, 1.0
	v_fmac_f32_e32 v104, v105, v104
	v_div_scale_f32 v105, vcc, v100, v97, v100
	v_mul_f32_e32 v108, v105, v104
	v_fma_f32 v109, -v101, v108, v105
	v_fmac_f32_e32 v108, v109, v104
	v_fma_f32 v101, -v101, v108, v105
	v_div_fmas_f32 v101, v101, v104, v108
	v_cvt_f32_f16_e32 v104, v230
	v_div_fixup_f32 v97, v101, v97, v100
	v_mul_f32_e32 v96, v97, v96
	v_med3_f32 v96, v96, s57, v194
	v_mul_f32_e32 v105, 0xbfb8aa3b, v104
	v_exp_f32_e32 v105, v105
	v_cvt_f16_f32_e32 v96, v96
	v_mov_b32_e32 v97, v106
	v_add_f32_e32 v105, 1.0, v105
	v_div_scale_f32 v108, s[8:9], v105, v105, v104
	v_rcp_f32_e32 v109, v108
	global_store_short v[162:163], v96, off
	v_mov_b32_e32 v96, v110
	v_pk_mul_f32 v[100:101], v[96:97], v[96:97]
	v_fma_f32 v162, -v108, v109, 1.0
	v_fmac_f32_e32 v109, v162, v109
	v_div_scale_f32 v162, vcc, v104, v105, v104
	v_mul_f32_e32 v163, v162, v109
	v_fma_f32 v164, -v108, v163, v162
	v_fmac_f32_e32 v163, v164, v109
	v_fma_f32 v108, -v108, v163, v162
	v_div_fmas_f32 v108, v108, v109, v163
	v_div_fixup_f32 v164, v108, v105, v104
	v_cvt_f32_f16_e32 v104, v229
	v_mov_b32_e32 v96, v102
	v_mov_b32_e32 v97, v98
	v_pk_mul_f32 v[96:97], v[96:97], v[96:97]
	v_mul_f32_e32 v105, 0xbfb8aa3b, v104
	v_exp_f32_e32 v105, v105
	s_nop 0
	v_add_f32_e32 v105, 1.0, v105
	v_div_scale_f32 v108, s[8:9], v105, v105, v104
	v_rcp_f32_e32 v109, v108
	s_nop 0
	v_fma_f32 v162, -v108, v109, 1.0
	v_fmac_f32_e32 v109, v162, v109
	v_div_scale_f32 v162, vcc, v104, v105, v104
	v_mul_f32_e32 v163, v162, v109
	v_fma_f32 v165, -v108, v163, v162
	v_fmac_f32_e32 v163, v165, v109
	v_fma_f32 v108, -v108, v163, v162
	v_div_fmas_f32 v108, v108, v109, v163
	v_div_fixup_f32 v165, v108, v105, v104
	v_cvt_f32_f16_e32 v104, v228
	v_mul_f32_e32 v105, 0xbfb8aa3b, v104
	v_exp_f32_e32 v105, v105
	s_nop 0
	v_add_f32_e32 v105, 1.0, v105
	v_div_scale_f32 v108, s[8:9], v105, v105, v104
	v_rcp_f32_e32 v109, v108
	s_nop 0
	v_fma_f32 v162, -v108, v109, 1.0
	v_fmac_f32_e32 v109, v162, v109
	v_div_scale_f32 v162, vcc, v104, v105, v104
	v_mul_f32_e32 v163, v162, v109
	v_fma_f32 v166, -v108, v163, v162
	v_fmac_f32_e32 v163, v166, v109
	v_fma_f32 v108, -v108, v163, v162
	v_div_fmas_f32 v108, v108, v109, v163
	v_div_fixup_f32 v166, v108, v105, v104
	v_cvt_f32_f16_e32 v104, v227
	v_mul_f32_e32 v105, 0xbfb8aa3b, v104
	v_exp_f32_e32 v105, v105
	s_nop 0
	v_add_f32_e32 v105, 1.0, v105
	v_div_scale_f32 v108, s[8:9], v105, v105, v104
	v_rcp_f32_e32 v109, v108
	s_nop 0
	v_fma_f32 v162, -v108, v109, 1.0
	v_fmac_f32_e32 v109, v162, v109
	v_div_scale_f32 v162, vcc, v104, v105, v104
	v_mul_f32_e32 v163, v162, v109
	v_fma_f32 v167, -v108, v163, v162
	v_fmac_f32_e32 v163, v167, v109
	v_fma_f32 v108, -v108, v163, v162
	v_div_fmas_f32 v108, v108, v109, v163
	v_div_fixup_f32 v167, v108, v105, v104
	v_mov_b32_e32 v104, v111
	v_mov_b32_e32 v105, v107
	v_pk_mul_f32 v[104:105], v[104:105], v[104:105]
	v_mov_b32_e32 v108, v103
	v_mov_b32_e32 v109, v99
	v_pk_mul_f32 v[108:109], v[108:109], v[108:109]
	v_mov_b32_e32 v162, v104
	v_mov_b32_e32 v163, v100
	v_mov_b32_e32 v100, v105
	v_pk_add_f32 v[100:101], v[162:163], v[100:101]
	v_mov_b32_e32 v104, v108
	v_mov_b32_e32 v105, v96
	v_pk_add_f32 v[100:101], v[100:101], v[104:105]
	v_mov_b32_e32 v96, v109
	v_pk_add_f32 v[96:97], v[100:101], v[96:97]
	s_nop 1
	v_mov_b32_dpp v101, v97 quad_perm:[1,0,3,2] row_mask:0xf bank_mask:0xf bound_ctrl:1
	v_mov_b32_dpp v100, v96 quad_perm:[1,0,3,2] row_mask:0xf bank_mask:0xf bound_ctrl:1
	v_pk_add_f32 v[96:97], v[96:97], v[100:101]
	s_nop 1
	v_mov_b32_dpp v101, v97 quad_perm:[2,3,0,1] row_mask:0xf bank_mask:0xf bound_ctrl:1
	v_mov_b32_dpp v100, v96 quad_perm:[2,3,0,1] row_mask:0xf bank_mask:0xf bound_ctrl:1
	v_pk_add_f32 v[96:97], v[96:97], v[100:101]
	s_nop 1
	v_mov_b32_dpp v101, v97 row_ror:4 row_mask:0xf bank_mask:0xf bound_ctrl:1
	v_mov_b32_dpp v100, v96 row_ror:4 row_mask:0xf bank_mask:0xf bound_ctrl:1
	v_pk_add_f32 v[96:97], v[96:97], v[100:101]
	s_nop 1
	v_mov_b32_dpp v101, v97 row_ror:8 row_mask:0xf bank_mask:0xf bound_ctrl:1
	v_mov_b32_dpp v100, v96 row_ror:8 row_mask:0xf bank_mask:0xf bound_ctrl:1
	v_pk_add_f32 v[96:97], v[96:97], v[100:101]
	s_nop 0
	v_pk_fma_f32 v[96:97], v[96:97], s[0:1], v[170:171] op_sel_hi:[1,0,0]
	s_nop 0
	v_mul_f32_e32 v100, 0x4b800000, v97
	v_cmp_gt_f32_e64 s[8:9], s49, v97
	v_cmp_gt_f32_e32 vcc, s49, v96
	s_nop 0
	v_cndmask_b32_e64 v97, v97, v100, s[8:9]
	v_rsq_f32_e32 v97, v97
	s_nop 0
	v_mul_f32_e32 v100, 0x45800000, v97
	v_cndmask_b32_e64 v97, v97, v100, s[8:9]
	v_mul_f32_e32 v100, v110, v97
	v_mul_f32_e32 v100, v238, v100
	v_mul_f32_e32 v100, v164, v100
	v_med3_f32 v100, v100, s57, v194
	v_cvt_f16_f32_e32 v100, v100
	global_store_short v[160:161], v100, off
	v_mul_f32_e32 v100, v106, v97
	v_mul_f32_e32 v100, v237, v100
	v_mul_f32_e32 v100, v165, v100
	v_med3_f32 v100, v100, s57, v194
	v_cvt_f16_f32_e32 v100, v100
	global_store_short v[158:159], v100, off
	v_mul_f32_e32 v100, v102, v97
	v_mul_f32_e32 v97, v98, v97
	v_mul_f32_e32 v97, v235, v97
	v_mul_f32_e32 v97, v167, v97
	v_med3_f32 v97, v97, s57, v194
	v_cvt_f16_f32_e32 v97, v97
	v_mul_f32_e32 v100, v236, v100
	v_mul_f32_e32 v100, v166, v100
	v_med3_f32 v100, v100, s57, v194
	global_store_short v[154:155], v97, off
	v_mul_f32_e32 v97, 0x4b800000, v96
	v_cndmask_b32_e32 v96, v96, v97, vcc
	v_rsq_f32_e32 v96, v96
	v_cvt_f16_f32_e32 v100, v100
	v_mul_f32_e32 v97, 0x45800000, v96
	v_cndmask_b32_e32 v96, v96, v97, vcc
	v_cvt_f32_f16_e32 v97, v226
	global_store_short v[156:157], v100, off
	v_mul_f32_e32 v98, v111, v96
	v_mul_f32_e32 v98, v238, v98
	v_mul_f32_e32 v100, 0xbfb8aa3b, v97
	v_exp_f32_e32 v100, v100
	s_nop 0
	v_add_f32_e32 v100, 1.0, v100
	v_div_scale_f32 v101, s[8:9], v100, v100, v97
	v_rcp_f32_e32 v102, v101
	s_nop 0
	v_fma_f32 v104, -v101, v102, 1.0
	v_fmac_f32_e32 v102, v104, v102
	v_div_scale_f32 v104, vcc, v97, v100, v97
	v_mul_f32_e32 v105, v104, v102
	v_fma_f32 v106, -v101, v105, v104
	v_fmac_f32_e32 v105, v106, v102
	v_fma_f32 v101, -v101, v105, v104
	v_div_fmas_f32 v101, v101, v102, v105
	v_div_fixup_f32 v97, v101, v100, v97
	v_mul_f32_e32 v97, v97, v98
	v_med3_f32 v97, v97, s57, v194
	v_cvt_f16_f32_e32 v97, v97
	v_mul_f32_e32 v98, v107, v96
	v_mul_f32_e32 v98, v237, v98
	global_store_short v[152:153], v97, off
	v_cvt_f32_f16_e32 v97, v225
	v_mul_f32_e32 v100, 0xbfb8aa3b, v97
	v_exp_f32_e32 v100, v100
	s_nop 0
	v_add_f32_e32 v100, 1.0, v100
	v_div_scale_f32 v101, s[8:9], v100, v100, v97
	v_rcp_f32_e32 v102, v101
	s_nop 0
	v_fma_f32 v104, -v101, v102, 1.0
	v_fmac_f32_e32 v102, v104, v102
	v_div_scale_f32 v104, vcc, v97, v100, v97
	v_mul_f32_e32 v105, v104, v102
	v_fma_f32 v106, -v101, v105, v104
	v_fmac_f32_e32 v105, v106, v102
	v_fma_f32 v101, -v101, v105, v104
	v_div_fmas_f32 v101, v101, v102, v105
	v_div_fixup_f32 v97, v101, v100, v97
	v_mul_f32_e32 v97, v97, v98
	v_med3_f32 v97, v97, s57, v194
	v_cvt_f16_f32_e32 v97, v97
	v_mul_f32_e32 v98, v103, v96
	v_mul_f32_e32 v98, v236, v98
	v_mul_f32_e32 v96, v99, v96
	global_store_short v[150:151], v97, off
	v_cvt_f32_f16_e32 v97, v224
	v_mul_f32_e32 v96, v235, v96
	v_mul_f32_e32 v100, 0xbfb8aa3b, v97
	v_exp_f32_e32 v100, v100
	s_nop 0
	v_add_f32_e32 v100, 1.0, v100
	v_div_scale_f32 v101, s[8:9], v100, v100, v97
	v_rcp_f32_e32 v102, v101
	s_nop 0
	v_fma_f32 v103, -v101, v102, 1.0
	v_fmac_f32_e32 v102, v103, v102
	v_div_scale_f32 v103, vcc, v97, v100, v97
	v_mul_f32_e32 v104, v103, v102
	v_fma_f32 v105, -v101, v104, v103
	v_fmac_f32_e32 v104, v105, v102
	v_fma_f32 v101, -v101, v104, v103
	v_div_fmas_f32 v101, v101, v102, v104
	v_div_fixup_f32 v97, v101, v100, v97
	v_mul_f32_e32 v97, v97, v98
	v_med3_f32 v97, v97, s57, v194
	v_cvt_f16_f32_e32 v97, v97
	global_store_short v[148:149], v97, off
	v_cvt_f32_f16_e32 v97, v223
	v_mul_f32_e32 v98, 0xbfb8aa3b, v97
	v_exp_f32_e32 v98, v98
	s_nop 0
	v_add_f32_e32 v98, 1.0, v98
	v_div_scale_f32 v99, s[8:9], v98, v98, v97
	v_rcp_f32_e32 v100, v99
	s_nop 0
	v_fma_f32 v101, -v99, v100, 1.0
	v_fmac_f32_e32 v100, v101, v100
	v_div_scale_f32 v101, vcc, v97, v98, v97
	v_mul_f32_e32 v102, v101, v100
	v_fma_f32 v103, -v99, v102, v101
	v_fmac_f32_e32 v102, v103, v100
	v_fma_f32 v99, -v99, v102, v101
	v_div_fmas_f32 v99, v99, v100, v102
	v_div_fixup_f32 v97, v99, v98, v97
	v_mul_f32_e32 v96, v97, v96
	v_med3_f32 v96, v96, s57, v194
	v_cvt_f16_f32_e32 v96, v96
	s_andn2_b64 vcc, exec, s[10:11]
	global_store_short v[146:147], v96, off
	ds_read_b128 v[96:99], v116 offset:55296
	ds_read_b128 v[240:243], v117 offset:36864
	ds_read_b128 v[244:247], v117 offset:39168
	ds_read_b128 v[252:255], v117 offset:41472
	s_waitcnt lgkmcnt(2)
	v_pk_mul_f32 v[82:83], v[82:83], v[112:113] op_sel_hi:[1,0]
	v_mul_f32_e64 v80, v80, v112
	v_mul_f32_e64 v81, v81, v112
	v_pk_mul_f32 v[86:87], v[86:87], v[112:113] op_sel_hi:[1,0]
	v_pk_mul_f32 v[84:85], v[84:85], v[112:113] op_sel_hi:[1,0]
	v_mul_f32_e64 v90, v90, v112
	v_mul_f32_e64 v91, v91, v112
	v_pk_mul_f32 v[88:89], v[88:89], v[112:113] op_sel_hi:[1,0]
	v_pk_mul_f32 v[94:95], v[94:95], v[112:113] op_sel_hi:[1,0]
	v_pk_mul_f32 v[92:93], v[92:93], v[112:113] op_sel_hi:[1,0]
	s_nop 1
	v_mfma_f32_16x16x32_f16 v[80:83], v[96:99], v[240:243], v[80:83]
	ds_read_b128 v[240:243], v117 offset:43776
	ds_read_b128 v[100:103], v116 offset:55360
	s_waitcnt lgkmcnt(3)
	v_mfma_f32_16x16x32_f16 v[84:87], v[96:99], v[244:247], v[84:87]
	ds_read_b128 v[244:247], v117 offset:36928
	s_waitcnt lgkmcnt(3)
	v_mfma_f32_16x16x32_f16 v[88:91], v[96:99], v[252:255], v[88:91]
	ds_read_b128 v[252:255], v117 offset:39232
	s_waitcnt lgkmcnt(3)
	v_mfma_f32_16x16x32_f16 v[92:95], v[96:99], v[240:243], v[92:95]
	ds_read_b128 v[240:243], v117 offset:41536
	s_waitcnt lgkmcnt(2)
	v_mfma_f32_16x16x32_f16 v[80:83], v[100:103], v[244:247], v[80:83]
	ds_read_b128 v[244:247], v117 offset:43840
	s_waitcnt lgkmcnt(2)
	v_mfma_f32_16x16x32_f16 v[84:87], v[100:103], v[252:255], v[84:87]
	s_waitcnt lgkmcnt(1)
	v_mfma_f32_16x16x32_f16 v[88:91], v[100:103], v[240:243], v[88:91]
	s_waitcnt lgkmcnt(0)
	s_barrier
	v_mfma_f32_16x16x32_f16 v[92:95], v[100:103], v[244:247], v[92:95]
	v_max_f32_e32 v96, v80, v80
	v_med3_f32 v96, v96, s57, v194
	v_cvt_f16_f32_e32 v96, v96
	ds_write_b16 v215, v96 offset:46080
	v_max_f32_e32 v96, v81, v81
	v_med3_f32 v96, v96, s57, v194
	v_cvt_f16_f32_e32 v96, v96
	ds_write_b16 v215, v96 offset:46224
	v_max_f32_e32 v96, v82, v82
	v_med3_f32 v96, v96, s57, v194
	v_cvt_f16_f32_e32 v96, v96
	ds_write_b16 v215, v96 offset:46368
	v_max_f32_e32 v96, v83, v83
	v_med3_f32 v96, v96, s57, v194
	v_cvt_f16_f32_e32 v96, v96
	ds_write_b16 v215, v96 offset:46512
	v_max_f32_e32 v96, v84, v84
	v_med3_f32 v96, v96, s57, v194
	v_cvt_f16_f32_e32 v96, v96
	ds_write_b16 v215, v96 offset:46112
	v_max_f32_e32 v96, v85, v85
	v_med3_f32 v96, v96, s57, v194
	v_cvt_f16_f32_e32 v96, v96
	ds_write_b16 v216, v96 offset:46224
	v_max_f32_e32 v96, v86, v86
	v_med3_f32 v96, v96, s57, v194
	v_cvt_f16_f32_e32 v96, v96
	ds_write_b16 v216, v96 offset:46368
	v_max_f32_e32 v96, v87, v87
	v_med3_f32 v96, v96, s57, v194
	v_cvt_f16_f32_e32 v96, v96
	ds_write_b16 v216, v96 offset:46512
	v_max_f32_e32 v96, v88, v88
	v_med3_f32 v96, v96, s57, v194
	v_cvt_f16_f32_e32 v96, v96
	ds_write_b16 v215, v96 offset:46144
	v_max_f32_e32 v96, v89, v89
	v_med3_f32 v96, v96, s57, v194
	v_cvt_f16_f32_e32 v96, v96
	ds_write_b16 v217, v96 offset:46224
	v_max_f32_e32 v96, v90, v90
	v_med3_f32 v96, v96, s57, v194
	v_cvt_f16_f32_e32 v96, v96
	ds_write_b16 v217, v96 offset:46368
	v_max_f32_e32 v96, v91, v91
	v_med3_f32 v96, v96, s57, v194
	v_cvt_f16_f32_e32 v96, v96
	ds_write_b16 v217, v96 offset:46512
	v_max_f32_e32 v96, v92, v92
	v_med3_f32 v96, v96, s57, v194
	v_cvt_f16_f32_e32 v96, v96
	ds_write_b16 v215, v96 offset:46176
	v_max_f32_e32 v96, v93, v93
	v_med3_f32 v96, v96, s57, v194
	v_cvt_f16_f32_e32 v96, v96
	ds_write_b16 v218, v96 offset:46224
	v_max_f32_e32 v96, v94, v94
	v_med3_f32 v96, v96, s57, v194
	v_cvt_f16_f32_e32 v96, v96
	ds_write_b16 v218, v96 offset:46368
	v_max_f32_e32 v96, v95, v95
	v_med3_f32 v96, v96, s57, v194
	v_cvt_f16_f32_e32 v96, v96
	ds_write_b16 v218, v96 offset:46512
	s_cbranch_vccnz .LBB0_520
	ds_write_b128 v220, v[56:59]
	ds_write_b128 v211, v[60:63]
	ds_write_b128 v221, v[64:67]
	ds_write_b128 v212, v[68:71]
	ds_write_b128 v222, v[72:75]
	ds_write_b128 v213, v[76:79]
	s_branch .LBB0_520
